# v47 with grid-size guards on the moved w_ffn_out range (phase-4 bounds and FFN-in tail only on the 256-workgroup grid)
# speedup vs baseline: 1.0040x; 1.0040x over previous
.LBB0_464:
	s_min_i32 s5, s84, 0x80
	v_readlane_b32 s0, v254, 0
	s_waitcnt vmcnt(0)
	v_lshrrev_b32_e32 v2, 6, v0
	s_mov_b32 s2, s0
	s_cmp_ge_i32 s0, s5
	s_mul_i32 s0, s0, 2
	v_add3_u32 v3, v2, s0, -1
	s_cselect_b64 vcc, -1, 0
	s_sub_i32 s0, s2, s5
	s_mul_i32 s4, s5, 2
	s_lshl_b32 s0, s0, 3
	s_add_i32 s0, s0, s4
	v_readlane_b32 s1, v254, 1
	v_add_u32_e32 v2, s0, v2
	v_add_u32_e32 v31, -64, v0
	s_movk_i32 s7, 0x80
	v_cmp_gt_u32_e64 s[0:1], s7, v31
	v_cndmask_b32_e32 v30, v3, v2, vcc
	s_mov_b32 s6, 0x18200
	s_cmpk_eq_u32 s84, 0x100
	s_cselect_b32 s6, 0x13200, s6
	s_or_b64 s[0:1], vcc, s[0:1]
	v_cmp_gt_i32_e32 vcc, s6, v30
	s_movk_i32 s3, 0x80
	s_and_b64 s[6:7], s[0:1], vcc
	s_and_saveexec_b64 s[0:1], s[6:7]
	s_cbranch_execz .LBB0_491
	s_sub_i32 s5, s84, s5
	v_lshlrev_b32_e32 v2, 8, v0
	s_lshl_b32 s33, s5, 3
	v_and_b32_e32 v2, 0x1c000, v2
	s_add_i32 s33, s33, s4
	v_add_u32_e32 v7, 0, v2
	v_lshlrev_b32_e32 v2, 4, v0
	v_and_b32_e32 v24, 0x70, v2
	v_lshlrev_b32_e32 v2, 3, v0
	s_add_u32 s6, s66, 0x8100000
	v_and_b32_e32 v2, 56, v2
	s_addc_u32 s7, s67, 0
	v_mul_u32_u24_e32 v6, 0x84, v2
	v_lshlrev_b32_e32 v2, 1, v2
	v_mov_b32_e32 v3, 0
	s_add_u32 s8, s66, 0x93400
	v_lshl_add_u64 v[12:13], s[66:67], 0, v[2:3]
	s_addc_u32 s9, s67, 0
	s_mov_b64 s[12:13], 0x6100000
	s_add_u32 s10, s66, 0xbc000
	v_lshl_add_u64 v[8:9], v[12:13], 0, s[12:13]
	s_mov_b64 s[12:13], 0x5100000
	s_mov_b64 s[4:5], 0x12d00000
	s_addc_u32 s11, s67, 0
	v_lshl_add_u64 v[10:11], v[12:13], 0, s[12:13]
	s_mov_b64 s[12:13], 0x4100000
	v_lshl_add_u64 v[4:5], v[12:13], 0, s[4:5]
	v_lshl_add_u64 v[12:13], v[12:13], 0, s[12:13]
	s_add_u32 s12, s66, 0x100000
	s_addc_u32 s13, s67, 0
	v_readlane_b32 s36, v254, 20
	v_lshrrev_b32_e32 v31, 3, v1
	s_add_u32 s14, s66, 0x8b400
	v_readlane_b32 s40, v254, 24
	v_readlane_b32 s41, v254, 25
	v_add_u32_e32 v26, v7, v24
	v_mul_u32_u24_e32 v27, 0x84, v31
	s_addc_u32 s15, s67, 0
	v_readlane_b32 s42, v254, 26
	v_readlane_b32 s43, v254, 27
	v_readlane_b32 s44, v254, 28
	v_readlane_b32 s45, v254, 29
	v_readlane_b32 s46, v254, 30
	v_readlane_b32 s47, v254, 31
	v_readlane_b32 s48, v254, 32
	v_readlane_b32 s49, v254, 33
	v_readlane_b32 s50, v254, 34
	v_readlane_b32 s51, v254, 35
	s_mov_b64 s[20:21], s[40:41]
	v_lshlrev_b32_e32 v2, 2, v31
	v_lshrrev_b32_e32 v1, 1, v1
	v_and_b32_e32 v40, 1, v0
	s_add_u32 s16, s66, 0xb4000
	v_mov_b32_e32 v25, v3
	v_readlane_b32 s37, v254, 21
	v_readlane_b32 s38, v254, 22
	v_readlane_b32 s39, v254, 23
	s_mov_b64 s[24:25], s[44:45]
	s_mov_b64 s[26:27], s[46:47]
	s_mov_b64 s[28:29], s[48:49]
	s_mov_b64 s[30:31], s[50:51]
	v_add_u32_e32 v44, v26, v27
	v_or_b32_e32 v32, 8, v31
	v_or_b32_e32 v33, 16, v31
	v_or_b32_e32 v34, 24, v31
	v_or_b32_e32 v35, 32, v31
	v_or_b32_e32 v36, 40, v31
	v_or_b32_e32 v37, 48, v31
	v_or_b32_e32 v38, 56, v31
	v_add3_u32 v39, v7, v6, v2
	v_lshlrev_b32_e32 v6, 5, v40
	v_lshl_add_u32 v41, v1, 2, v7
	v_mul_u32_u24_e32 v42, 0x1080, v40
	v_mov_b32_e32 v7, v3
	v_cmp_eq_u32_e64 s[4:5], 0, v40
	s_addc_u32 s17, s67, 0
	v_lshl_add_u64 v[14:15], s[60:61], 0, v[24:25]
	v_lshl_add_u64 v[16:17], s[54:55], 0, v[24:25]
	s_mov_b64 s[22:23], s[42:43]
	v_lshl_add_u64 v[18:19], s[30:31], 0, v[24:25]
	v_lshl_add_u64 v[20:21], s[26:27], 0, v[24:25]
	v_lshl_add_u64 v[22:23], s[24:25], 0, v[24:25]
	v_lshl_add_u64 v[24:25], s[28:29], 0, v[24:25]
	v_lshlrev_b32_e32 v43, 5, v30
	s_lshl_b32 s34, s33, 5
	s_mov_b64 s[18:19], 0
	s_movk_i32 s35, 0x3fff
	s_movk_i32 s36, 0x4fff
	s_movk_i32 s37, 0x5fff
	s_movk_i32 s38, 0x7fff
	s_mov_b32 s39, 0x12bff
	v_add_u32_e32 v45, 0x420, v44
	v_add_u32_e32 v46, 0x428, v44
	v_add_u32_e32 v47, 0x840, v44
	v_add_u32_e32 v48, 0x848, v44
	v_add_u32_e32 v49, 0xc60, v44
	v_add_u32_e32 v50, 0xc68, v44
	s_mov_b32 s40, 0xffff0000
	s_mov_b32 s41, 0xbe83
	s_movk_i32 s42, 0x2b0
	s_movk_i32 s43, 0x2a80
	s_mov_b32 s44, 0x42fe0000
	s_mov_b32 s45, 0xc0c0500
	s_mov_b32 s46, 0x181ff
	s_cmpk_eq_u32 s84, 0x100
	s_cselect_b32 s46, 0x131ff, s46
	v_add_u32_e32 v51, 0x1080, v44
	v_add_u32_e32 v52, 0x1088, v44
	v_add_u32_e32 v53, 0x14a0, v44
	v_add_u32_e32 v54, 0x14a8, v44
	v_add_u32_e32 v55, 0x18c0, v44
	s_branch .LBB0_468

.LBB0_1906:
	s_waitcnt vmcnt(0)
	s_mov_b32 s2, s86
	s_barrier
	s_cmpk_eq_u32 s84, 0x100
	s_cbranch_scc0 .Lwf_done
	v_readlane_b32 s94, v254, 0
	v_readfirstlane_b32 s95, v0
	s_nop 3
	s_cmpk_lt_u32 s94, 0x80
	s_cbranch_scc1 .Lwf_done
	s_lshr_b32 s95, s95, 6
	s_sub_u32 s94, s94, 0x80
	s_lshl_b32 s94, s94, 3
	s_add_u32 s94, s94, s95
	v_readlane_b32 s96, v254, 2
	v_readlane_b32 s97, v254, 3
	s_nop 3
	s_sub_u32 s96, s96, 0x28
	s_subb_u32 s97, s97, 0
	s_load_dwordx2 s[100:101], s[96:97], 0x0
	s_add_u32 s94, s94, 0x600
	v_and_b32_e32 v2, 63, v0
	v_lshrrev_b32_e32 v3, 3, v2
	v_and_b32_e32 v4, 7, v2
	v_lshlrev_b32_e32 v5, 14, v3
	v_lshl_add_u32 v5, v4, 4, v5
	v_add_u32_e32 v6, 0x0, v5
	v_add_u32_e32 v7, 0x20000, v5
	v_add_u32_e32 v8, 0x40000, v5
	v_add_u32_e32 v9, 0x60000, v5
	v_add_u32_e32 v10, 0x80000, v5
	v_add_u32_e32 v11, 0xa0000, v5
	v_add_u32_e32 v12, 0xc0000, v5
	v_add_u32_e32 v13, 0xe0000, v5
	s_lshl_b32 s95, s95, 14
	v_mul_u32_u24_e32 v14, 0x84, v3
	v_lshl_add_u32 v14, v4, 4, v14
	v_add_u32_e32 v14, s95, v14
	v_mul_u32_u24_e32 v15, 0x420, v4
	v_lshl_add_u32 v15, v3, 2, v15
	v_add_u32_e32 v15, s95, v15
	v_mul_u32_u24_e32 v16, 0x5600, v3
	v_lshl_add_u32 v16, v4, 4, v16
	v_add_u32_e32 v17, 0x2b000, v16
	v_add_u32_e32 v18, 0x56000, v16
	v_add_u32_e32 v19, 0x81000, v16
	s_waitcnt lgkmcnt(0)
	s_mov_b32 s95, s94
	s_lshr_b32 vcc_lo, s95, 7
	s_and_b32 vcc_hi, s95, 0x7f
	s_lshl_b32 vcc_lo, vcc_lo, 20
	s_lshl_b32 vcc_hi, vcc_hi, 7
	s_add_u32 s96, s100, vcc_lo
	s_addc_u32 s97, s101, 0
	s_add_u32 s96, s96, vcc_hi
	s_addc_u32 s97, s97, 0
	global_load_dwordx4 v[20:23], v6, s[96:97]
	global_load_dwordx4 v[24:27], v7, s[96:97]
	global_load_dwordx4 v[28:31], v8, s[96:97]
	global_load_dwordx4 v[32:35], v9, s[96:97]
	global_load_dwordx4 v[36:39], v10, s[96:97]
	global_load_dwordx4 v[40:43], v11, s[96:97]
	global_load_dwordx4 v[44:47], v12, s[96:97]
	global_load_dwordx4 v[48:51], v13, s[96:97]
	s_add_u32 s95, s94, 0x400
	s_lshr_b32 vcc_lo, s95, 7
	s_and_b32 vcc_hi, s95, 0x7f
	s_lshl_b32 vcc_lo, vcc_lo, 20
	s_lshl_b32 vcc_hi, vcc_hi, 7
	s_add_u32 s96, s100, vcc_lo
	s_addc_u32 s97, s101, 0
	s_add_u32 s96, s96, vcc_hi
	s_addc_u32 s97, s97, 0
	global_load_dwordx4 v[100:103], v6, s[96:97]
	global_load_dwordx4 v[104:107], v7, s[96:97]
	global_load_dwordx4 v[108:111], v8, s[96:97]
	global_load_dwordx4 v[112:115], v9, s[96:97]
	global_load_dwordx4 v[116:119], v10, s[96:97]
	global_load_dwordx4 v[120:123], v11, s[96:97]
	global_load_dwordx4 v[124:127], v12, s[96:97]
	global_load_dwordx4 v[128:131], v13, s[96:97]
	s_waitcnt vmcnt(15)
	ds_write_b32 v14, v20 offset:0
	ds_write_b32 v14, v21 offset:4
	ds_write_b32 v14, v22 offset:8
	ds_write_b32 v14, v23 offset:12
	s_waitcnt vmcnt(14)
	ds_write_b32 v14, v24 offset:1056
	ds_write_b32 v14, v25 offset:1060
	ds_write_b32 v14, v26 offset:1064
	ds_write_b32 v14, v27 offset:1068
	s_waitcnt vmcnt(13)
	ds_write_b32 v14, v28 offset:2112
	ds_write_b32 v14, v29 offset:2116
	ds_write_b32 v14, v30 offset:2120
	ds_write_b32 v14, v31 offset:2124
	s_waitcnt vmcnt(12)
	ds_write_b32 v14, v32 offset:3168
	ds_write_b32 v14, v33 offset:3172
	ds_write_b32 v14, v34 offset:3176
	ds_write_b32 v14, v35 offset:3180
	s_waitcnt vmcnt(11)
	ds_write_b32 v14, v36 offset:4224
	ds_write_b32 v14, v37 offset:4228
	ds_write_b32 v14, v38 offset:4232
	ds_write_b32 v14, v39 offset:4236
	s_waitcnt vmcnt(10)
	ds_write_b32 v14, v40 offset:5280
	ds_write_b32 v14, v41 offset:5284
	ds_write_b32 v14, v42 offset:5288
	ds_write_b32 v14, v43 offset:5292
	s_waitcnt vmcnt(9)
	ds_write_b32 v14, v44 offset:6336
	ds_write_b32 v14, v45 offset:6340
	ds_write_b32 v14, v46 offset:6344
	ds_write_b32 v14, v47 offset:6348
	s_waitcnt vmcnt(8)
	ds_write_b32 v14, v48 offset:7392
	ds_write_b32 v14, v49 offset:7396
	ds_write_b32 v14, v50 offset:7400
	ds_write_b32 v14, v51 offset:7404
	s_add_u32 s95, s94, 0x800
	s_lshr_b32 vcc_lo, s95, 7
	s_and_b32 vcc_hi, s95, 0x7f
	s_lshl_b32 vcc_lo, vcc_lo, 20
	s_lshl_b32 vcc_hi, vcc_hi, 7
	s_add_u32 s96, s100, vcc_lo
	s_addc_u32 s97, s101, 0
	s_add_u32 s96, s96, vcc_hi
	s_addc_u32 s97, s97, 0
	global_load_dwordx4 v[20:23], v6, s[96:97]
	global_load_dwordx4 v[24:27], v7, s[96:97]
	global_load_dwordx4 v[28:31], v8, s[96:97]
	global_load_dwordx4 v[32:35], v9, s[96:97]
	global_load_dwordx4 v[36:39], v10, s[96:97]
	global_load_dwordx4 v[40:43], v11, s[96:97]
	global_load_dwordx4 v[44:47], v12, s[96:97]
	global_load_dwordx4 v[48:51], v13, s[96:97]
	ds_read2_b32 v[52:53], v15 offset0:0 offset1:33
	ds_read2_b32 v[54:55], v15 offset0:66 offset1:99
	ds_read2_b32 v[56:57], v15 offset0:132 offset1:165
	ds_read2_b32 v[58:59], v15 offset0:198 offset1:231
	ds_read2_b32 v[60:61], v15 offset0:8 offset1:41
	ds_read2_b32 v[62:63], v15 offset0:74 offset1:107
	ds_read2_b32 v[64:65], v15 offset0:140 offset1:173
	ds_read2_b32 v[66:67], v15 offset0:206 offset1:239
	ds_read2_b32 v[68:69], v15 offset0:16 offset1:49
	ds_read2_b32 v[70:71], v15 offset0:82 offset1:115
	ds_read2_b32 v[72:73], v15 offset0:148 offset1:181
	ds_read2_b32 v[74:75], v15 offset0:214 offset1:247
	ds_read2_b32 v[76:77], v15 offset0:24 offset1:57
	ds_read2_b32 v[78:79], v15 offset0:90 offset1:123
	ds_read2_b32 v[80:81], v15 offset0:156 offset1:189
	ds_read2_b32 v[82:83], v15 offset0:222 offset1:255
	s_mov_b32 s95, s94
	s_lshr_b32 vcc_lo, s95, 7
	s_and_b32 vcc_hi, s95, 0x7f
	s_mul_i32 vcc_hi, vcc_hi, 0xac000
	s_lshl_b32 vcc_lo, vcc_lo, 7
	s_add_u32 s98, s66, 0x12d00000
	s_addc_u32 s99, s67, 0
	s_add_u32 s98, s98, vcc_hi
	s_addc_u32 s99, s99, 0
	s_add_u32 s98, s98, vcc_lo
	s_addc_u32 s99, s99, 0
	s_waitcnt lgkmcnt(0)
	v_cvt_pk_bf16_f32 v84, v52, v53
	v_cvt_pk_bf16_f32 v85, v54, v55
	v_cvt_pk_bf16_f32 v86, v56, v57
	v_cvt_pk_bf16_f32 v87, v58, v59
	v_cvt_pk_bf16_f32 v88, v60, v61
	v_cvt_pk_bf16_f32 v89, v62, v63
	v_cvt_pk_bf16_f32 v90, v64, v65
	v_cvt_pk_bf16_f32 v91, v66, v67
	v_cvt_pk_bf16_f32 v92, v68, v69
	v_cvt_pk_bf16_f32 v93, v70, v71
	v_cvt_pk_bf16_f32 v94, v72, v73
	v_cvt_pk_bf16_f32 v95, v74, v75
	v_cvt_pk_bf16_f32 v96, v76, v77
	v_cvt_pk_bf16_f32 v97, v78, v79
	v_cvt_pk_bf16_f32 v98, v80, v81
	v_cvt_pk_bf16_f32 v99, v82, v83
	global_store_dwordx4 v16, v[84:87], s[98:99]
	global_store_dwordx4 v17, v[88:91], s[98:99]
	global_store_dwordx4 v18, v[92:95], s[98:99]
	global_store_dwordx4 v19, v[96:99], s[98:99]
	s_waitcnt vmcnt(19)
	ds_write_b32 v14, v100 offset:0
	ds_write_b32 v14, v101 offset:4
	ds_write_b32 v14, v102 offset:8
	ds_write_b32 v14, v103 offset:12
	s_waitcnt vmcnt(18)
	ds_write_b32 v14, v104 offset:1056
	ds_write_b32 v14, v105 offset:1060
	ds_write_b32 v14, v106 offset:1064
	ds_write_b32 v14, v107 offset:1068
	s_waitcnt vmcnt(17)
	ds_write_b32 v14, v108 offset:2112
	ds_write_b32 v14, v109 offset:2116
	ds_write_b32 v14, v110 offset:2120
	ds_write_b32 v14, v111 offset:2124
	s_waitcnt vmcnt(16)
	ds_write_b32 v14, v112 offset:3168
	ds_write_b32 v14, v113 offset:3172
	ds_write_b32 v14, v114 offset:3176
	ds_write_b32 v14, v115 offset:3180
	s_waitcnt vmcnt(15)
	ds_write_b32 v14, v116 offset:4224
	ds_write_b32 v14, v117 offset:4228
	ds_write_b32 v14, v118 offset:4232
	ds_write_b32 v14, v119 offset:4236
	s_waitcnt vmcnt(14)
	ds_write_b32 v14, v120 offset:5280
	ds_write_b32 v14, v121 offset:5284
	ds_write_b32 v14, v122 offset:5288
	ds_write_b32 v14, v123 offset:5292
	s_waitcnt vmcnt(13)
	ds_write_b32 v14, v124 offset:6336
	ds_write_b32 v14, v125 offset:6340
	ds_write_b32 v14, v126 offset:6344
	ds_write_b32 v14, v127 offset:6348
	s_waitcnt vmcnt(12)
	ds_write_b32 v14, v128 offset:7392
	ds_write_b32 v14, v129 offset:7396
	ds_write_b32 v14, v130 offset:7400
	ds_write_b32 v14, v131 offset:7404
	s_add_u32 s95, s94, 0xc00
	s_lshr_b32 vcc_lo, s95, 7
	s_and_b32 vcc_hi, s95, 0x7f
	s_lshl_b32 vcc_lo, vcc_lo, 20
	s_lshl_b32 vcc_hi, vcc_hi, 7
	s_add_u32 s96, s100, vcc_lo
	s_addc_u32 s97, s101, 0
	s_add_u32 s96, s96, vcc_hi
	s_addc_u32 s97, s97, 0
	global_load_dwordx4 v[100:103], v6, s[96:97]
	global_load_dwordx4 v[104:107], v7, s[96:97]
	global_load_dwordx4 v[108:111], v8, s[96:97]
	global_load_dwordx4 v[112:115], v9, s[96:97]
	global_load_dwordx4 v[116:119], v10, s[96:97]
	global_load_dwordx4 v[120:123], v11, s[96:97]
	global_load_dwordx4 v[124:127], v12, s[96:97]
	global_load_dwordx4 v[128:131], v13, s[96:97]
	ds_read2_b32 v[52:53], v15 offset0:0 offset1:33
	ds_read2_b32 v[54:55], v15 offset0:66 offset1:99
	ds_read2_b32 v[56:57], v15 offset0:132 offset1:165
	ds_read2_b32 v[58:59], v15 offset0:198 offset1:231
	ds_read2_b32 v[60:61], v15 offset0:8 offset1:41
	ds_read2_b32 v[62:63], v15 offset0:74 offset1:107
	ds_read2_b32 v[64:65], v15 offset0:140 offset1:173
	ds_read2_b32 v[66:67], v15 offset0:206 offset1:239
	ds_read2_b32 v[68:69], v15 offset0:16 offset1:49
	ds_read2_b32 v[70:71], v15 offset0:82 offset1:115
	ds_read2_b32 v[72:73], v15 offset0:148 offset1:181
	ds_read2_b32 v[74:75], v15 offset0:214 offset1:247
	ds_read2_b32 v[76:77], v15 offset0:24 offset1:57
	ds_read2_b32 v[78:79], v15 offset0:90 offset1:123
	ds_read2_b32 v[80:81], v15 offset0:156 offset1:189
	ds_read2_b32 v[82:83], v15 offset0:222 offset1:255
	s_add_u32 s95, s94, 0x400
	s_lshr_b32 vcc_lo, s95, 7
	s_and_b32 vcc_hi, s95, 0x7f
	s_mul_i32 vcc_hi, vcc_hi, 0xac000
	s_lshl_b32 vcc_lo, vcc_lo, 7
	s_add_u32 s98, s66, 0x12d00000
	s_addc_u32 s99, s67, 0
	s_add_u32 s98, s98, vcc_hi
	s_addc_u32 s99, s99, 0
	s_add_u32 s98, s98, vcc_lo
	s_addc_u32 s99, s99, 0
	s_waitcnt lgkmcnt(0)
	v_cvt_pk_bf16_f32 v84, v52, v53
	v_cvt_pk_bf16_f32 v85, v54, v55
	v_cvt_pk_bf16_f32 v86, v56, v57
	v_cvt_pk_bf16_f32 v87, v58, v59
	v_cvt_pk_bf16_f32 v88, v60, v61
	v_cvt_pk_bf16_f32 v89, v62, v63
	v_cvt_pk_bf16_f32 v90, v64, v65
	v_cvt_pk_bf16_f32 v91, v66, v67
	v_cvt_pk_bf16_f32 v92, v68, v69
	v_cvt_pk_bf16_f32 v93, v70, v71
	v_cvt_pk_bf16_f32 v94, v72, v73
	v_cvt_pk_bf16_f32 v95, v74, v75
	v_cvt_pk_bf16_f32 v96, v76, v77
	v_cvt_pk_bf16_f32 v97, v78, v79
	v_cvt_pk_bf16_f32 v98, v80, v81
	v_cvt_pk_bf16_f32 v99, v82, v83
	global_store_dwordx4 v16, v[84:87], s[98:99]
	global_store_dwordx4 v17, v[88:91], s[98:99]
	global_store_dwordx4 v18, v[92:95], s[98:99]
	global_store_dwordx4 v19, v[96:99], s[98:99]
	s_waitcnt vmcnt(23)
	ds_write_b32 v14, v20 offset:0
	ds_write_b32 v14, v21 offset:4
	ds_write_b32 v14, v22 offset:8
	ds_write_b32 v14, v23 offset:12
	s_waitcnt vmcnt(22)
	ds_write_b32 v14, v24 offset:1056
	ds_write_b32 v14, v25 offset:1060
	ds_write_b32 v14, v26 offset:1064
	ds_write_b32 v14, v27 offset:1068
	s_waitcnt vmcnt(21)
	ds_write_b32 v14, v28 offset:2112
	ds_write_b32 v14, v29 offset:2116
	ds_write_b32 v14, v30 offset:2120
	ds_write_b32 v14, v31 offset:2124
	s_waitcnt vmcnt(20)
	ds_write_b32 v14, v32 offset:3168
	ds_write_b32 v14, v33 offset:3172
	ds_write_b32 v14, v34 offset:3176
	ds_write_b32 v14, v35 offset:3180
	s_waitcnt vmcnt(19)
	ds_write_b32 v14, v36 offset:4224
	ds_write_b32 v14, v37 offset:4228
	ds_write_b32 v14, v38 offset:4232
	ds_write_b32 v14, v39 offset:4236
	s_waitcnt vmcnt(18)
	ds_write_b32 v14, v40 offset:5280
	ds_write_b32 v14, v41 offset:5284
	ds_write_b32 v14, v42 offset:5288
	ds_write_b32 v14, v43 offset:5292
	s_waitcnt vmcnt(17)
	ds_write_b32 v14, v44 offset:6336
	ds_write_b32 v14, v45 offset:6340
	ds_write_b32 v14, v46 offset:6344
	ds_write_b32 v14, v47 offset:6348
	s_waitcnt vmcnt(16)
	ds_write_b32 v14, v48 offset:7392
	ds_write_b32 v14, v49 offset:7396
	ds_write_b32 v14, v50 offset:7400
	ds_write_b32 v14, v51 offset:7404
	s_add_u32 s95, s94, 0x1000
	s_lshr_b32 vcc_lo, s95, 7
	s_and_b32 vcc_hi, s95, 0x7f
	s_lshl_b32 vcc_lo, vcc_lo, 20
	s_lshl_b32 vcc_hi, vcc_hi, 7
	s_add_u32 s96, s100, vcc_lo
	s_addc_u32 s97, s101, 0
	s_add_u32 s96, s96, vcc_hi
	s_addc_u32 s97, s97, 0
	global_load_dwordx4 v[20:23], v6, s[96:97]
	global_load_dwordx4 v[24:27], v7, s[96:97]
	global_load_dwordx4 v[28:31], v8, s[96:97]
	global_load_dwordx4 v[32:35], v9, s[96:97]
	global_load_dwordx4 v[36:39], v10, s[96:97]
	global_load_dwordx4 v[40:43], v11, s[96:97]
	global_load_dwordx4 v[44:47], v12, s[96:97]
	global_load_dwordx4 v[48:51], v13, s[96:97]
	ds_read2_b32 v[52:53], v15 offset0:0 offset1:33
	ds_read2_b32 v[54:55], v15 offset0:66 offset1:99
	ds_read2_b32 v[56:57], v15 offset0:132 offset1:165
	ds_read2_b32 v[58:59], v15 offset0:198 offset1:231
	ds_read2_b32 v[60:61], v15 offset0:8 offset1:41
	ds_read2_b32 v[62:63], v15 offset0:74 offset1:107
	ds_read2_b32 v[64:65], v15 offset0:140 offset1:173
	ds_read2_b32 v[66:67], v15 offset0:206 offset1:239
	ds_read2_b32 v[68:69], v15 offset0:16 offset1:49
	ds_read2_b32 v[70:71], v15 offset0:82 offset1:115
	ds_read2_b32 v[72:73], v15 offset0:148 offset1:181
	ds_read2_b32 v[74:75], v15 offset0:214 offset1:247
	ds_read2_b32 v[76:77], v15 offset0:24 offset1:57
	ds_read2_b32 v[78:79], v15 offset0:90 offset1:123
	ds_read2_b32 v[80:81], v15 offset0:156 offset1:189
	ds_read2_b32 v[82:83], v15 offset0:222 offset1:255
	s_add_u32 s95, s94, 0x800
	s_lshr_b32 vcc_lo, s95, 7
	s_and_b32 vcc_hi, s95, 0x7f
	s_mul_i32 vcc_hi, vcc_hi, 0xac000
	s_lshl_b32 vcc_lo, vcc_lo, 7
	s_add_u32 s98, s66, 0x12d00000
	s_addc_u32 s99, s67, 0
	s_add_u32 s98, s98, vcc_hi
	s_addc_u32 s99, s99, 0
	s_add_u32 s98, s98, vcc_lo
	s_addc_u32 s99, s99, 0
	s_waitcnt lgkmcnt(0)
	v_cvt_pk_bf16_f32 v84, v52, v53
	v_cvt_pk_bf16_f32 v85, v54, v55
	v_cvt_pk_bf16_f32 v86, v56, v57
	v_cvt_pk_bf16_f32 v87, v58, v59
	v_cvt_pk_bf16_f32 v88, v60, v61
	v_cvt_pk_bf16_f32 v89, v62, v63
	v_cvt_pk_bf16_f32 v90, v64, v65
	v_cvt_pk_bf16_f32 v91, v66, v67
	v_cvt_pk_bf16_f32 v92, v68, v69
	v_cvt_pk_bf16_f32 v93, v70, v71
	v_cvt_pk_bf16_f32 v94, v72, v73
	v_cvt_pk_bf16_f32 v95, v74, v75
	v_cvt_pk_bf16_f32 v96, v76, v77
	v_cvt_pk_bf16_f32 v97, v78, v79
	v_cvt_pk_bf16_f32 v98, v80, v81
	v_cvt_pk_bf16_f32 v99, v82, v83
	global_store_dwordx4 v16, v[84:87], s[98:99]
	global_store_dwordx4 v17, v[88:91], s[98:99]
	global_store_dwordx4 v18, v[92:95], s[98:99]
	global_store_dwordx4 v19, v[96:99], s[98:99]
	s_waitcnt vmcnt(23)
	ds_write_b32 v14, v100 offset:0
	ds_write_b32 v14, v101 offset:4
	ds_write_b32 v14, v102 offset:8
	ds_write_b32 v14, v103 offset:12
	s_waitcnt vmcnt(22)
	ds_write_b32 v14, v104 offset:1056
	ds_write_b32 v14, v105 offset:1060
	ds_write_b32 v14, v106 offset:1064
	ds_write_b32 v14, v107 offset:1068
	s_waitcnt vmcnt(21)
	ds_write_b32 v14, v108 offset:2112
	ds_write_b32 v14, v109 offset:2116
	ds_write_b32 v14, v110 offset:2120
	ds_write_b32 v14, v111 offset:2124
	s_waitcnt vmcnt(20)
	ds_write_b32 v14, v112 offset:3168
	ds_write_b32 v14, v113 offset:3172
	ds_write_b32 v14, v114 offset:3176
	ds_write_b32 v14, v115 offset:3180
	s_waitcnt vmcnt(19)
	ds_write_b32 v14, v116 offset:4224
	ds_write_b32 v14, v117 offset:4228
	ds_write_b32 v14, v118 offset:4232
	ds_write_b32 v14, v119 offset:4236
	s_waitcnt vmcnt(18)
	ds_write_b32 v14, v120 offset:5280
	ds_write_b32 v14, v121 offset:5284
	ds_write_b32 v14, v122 offset:5288
	ds_write_b32 v14, v123 offset:5292
	s_waitcnt vmcnt(17)
	ds_write_b32 v14, v124 offset:6336
	ds_write_b32 v14, v125 offset:6340
	ds_write_b32 v14, v126 offset:6344
	ds_write_b32 v14, v127 offset:6348
	s_waitcnt vmcnt(16)
	ds_write_b32 v14, v128 offset:7392
	ds_write_b32 v14, v129 offset:7396
	ds_write_b32 v14, v130 offset:7400
	ds_write_b32 v14, v131 offset:7404
	s_add_u32 s95, s94, 0x1400
	s_lshr_b32 vcc_lo, s95, 7
	s_and_b32 vcc_hi, s95, 0x7f
	s_lshl_b32 vcc_lo, vcc_lo, 20
	s_lshl_b32 vcc_hi, vcc_hi, 7
	s_add_u32 s96, s100, vcc_lo
	s_addc_u32 s97, s101, 0
	s_add_u32 s96, s96, vcc_hi
	s_addc_u32 s97, s97, 0
	global_load_dwordx4 v[100:103], v6, s[96:97]
	global_load_dwordx4 v[104:107], v7, s[96:97]
	global_load_dwordx4 v[108:111], v8, s[96:97]
	global_load_dwordx4 v[112:115], v9, s[96:97]
	global_load_dwordx4 v[116:119], v10, s[96:97]
	global_load_dwordx4 v[120:123], v11, s[96:97]
	global_load_dwordx4 v[124:127], v12, s[96:97]
	global_load_dwordx4 v[128:131], v13, s[96:97]
	ds_read2_b32 v[52:53], v15 offset0:0 offset1:33
	ds_read2_b32 v[54:55], v15 offset0:66 offset1:99
	ds_read2_b32 v[56:57], v15 offset0:132 offset1:165
	ds_read2_b32 v[58:59], v15 offset0:198 offset1:231
	ds_read2_b32 v[60:61], v15 offset0:8 offset1:41
	ds_read2_b32 v[62:63], v15 offset0:74 offset1:107
	ds_read2_b32 v[64:65], v15 offset0:140 offset1:173
	ds_read2_b32 v[66:67], v15 offset0:206 offset1:239
	ds_read2_b32 v[68:69], v15 offset0:16 offset1:49
	ds_read2_b32 v[70:71], v15 offset0:82 offset1:115
	ds_read2_b32 v[72:73], v15 offset0:148 offset1:181
	ds_read2_b32 v[74:75], v15 offset0:214 offset1:247
	ds_read2_b32 v[76:77], v15 offset0:24 offset1:57
	ds_read2_b32 v[78:79], v15 offset0:90 offset1:123
	ds_read2_b32 v[80:81], v15 offset0:156 offset1:189
	ds_read2_b32 v[82:83], v15 offset0:222 offset1:255
	s_add_u32 s95, s94, 0xc00
	s_lshr_b32 vcc_lo, s95, 7
	s_and_b32 vcc_hi, s95, 0x7f
	s_mul_i32 vcc_hi, vcc_hi, 0xac000
	s_lshl_b32 vcc_lo, vcc_lo, 7
	s_add_u32 s98, s66, 0x12d00000
	s_addc_u32 s99, s67, 0
	s_add_u32 s98, s98, vcc_hi
	s_addc_u32 s99, s99, 0
	s_add_u32 s98, s98, vcc_lo
	s_addc_u32 s99, s99, 0
	s_waitcnt lgkmcnt(0)
	v_cvt_pk_bf16_f32 v84, v52, v53
	v_cvt_pk_bf16_f32 v85, v54, v55
	v_cvt_pk_bf16_f32 v86, v56, v57
	v_cvt_pk_bf16_f32 v87, v58, v59
	v_cvt_pk_bf16_f32 v88, v60, v61
	v_cvt_pk_bf16_f32 v89, v62, v63
	v_cvt_pk_bf16_f32 v90, v64, v65
	v_cvt_pk_bf16_f32 v91, v66, v67
	v_cvt_pk_bf16_f32 v92, v68, v69
	v_cvt_pk_bf16_f32 v93, v70, v71
	v_cvt_pk_bf16_f32 v94, v72, v73
	v_cvt_pk_bf16_f32 v95, v74, v75
	v_cvt_pk_bf16_f32 v96, v76, v77
	v_cvt_pk_bf16_f32 v97, v78, v79
	v_cvt_pk_bf16_f32 v98, v80, v81
	v_cvt_pk_bf16_f32 v99, v82, v83
	global_store_dwordx4 v16, v[84:87], s[98:99]
	global_store_dwordx4 v17, v[88:91], s[98:99]
	global_store_dwordx4 v18, v[92:95], s[98:99]
	global_store_dwordx4 v19, v[96:99], s[98:99]
	s_waitcnt vmcnt(23)
	ds_write_b32 v14, v20 offset:0
	ds_write_b32 v14, v21 offset:4
	ds_write_b32 v14, v22 offset:8
	ds_write_b32 v14, v23 offset:12
	s_waitcnt vmcnt(22)
	ds_write_b32 v14, v24 offset:1056
	ds_write_b32 v14, v25 offset:1060
	ds_write_b32 v14, v26 offset:1064
	ds_write_b32 v14, v27 offset:1068
	s_waitcnt vmcnt(21)
	ds_write_b32 v14, v28 offset:2112
	ds_write_b32 v14, v29 offset:2116
	ds_write_b32 v14, v30 offset:2120
	ds_write_b32 v14, v31 offset:2124
	s_waitcnt vmcnt(20)
	ds_write_b32 v14, v32 offset:3168
	ds_write_b32 v14, v33 offset:3172
	ds_write_b32 v14, v34 offset:3176
	ds_write_b32 v14, v35 offset:3180
	s_waitcnt vmcnt(19)
	ds_write_b32 v14, v36 offset:4224
	ds_write_b32 v14, v37 offset:4228
	ds_write_b32 v14, v38 offset:4232
	ds_write_b32 v14, v39 offset:4236
	s_waitcnt vmcnt(18)
	ds_write_b32 v14, v40 offset:5280
	ds_write_b32 v14, v41 offset:5284
	ds_write_b32 v14, v42 offset:5288
	ds_write_b32 v14, v43 offset:5292
	s_waitcnt vmcnt(17)
	ds_write_b32 v14, v44 offset:6336
	ds_write_b32 v14, v45 offset:6340
	ds_write_b32 v14, v46 offset:6344
	ds_write_b32 v14, v47 offset:6348
	s_waitcnt vmcnt(16)
	ds_write_b32 v14, v48 offset:7392
	ds_write_b32 v14, v49 offset:7396
	ds_write_b32 v14, v50 offset:7400
	ds_write_b32 v14, v51 offset:7404
	s_add_u32 s95, s94, 0x1800
	s_lshr_b32 vcc_lo, s95, 7
	s_and_b32 vcc_hi, s95, 0x7f
	s_lshl_b32 vcc_lo, vcc_lo, 20
	s_lshl_b32 vcc_hi, vcc_hi, 7
	s_add_u32 s96, s100, vcc_lo
	s_addc_u32 s97, s101, 0
	s_add_u32 s96, s96, vcc_hi
	s_addc_u32 s97, s97, 0
	global_load_dwordx4 v[20:23], v6, s[96:97]
	global_load_dwordx4 v[24:27], v7, s[96:97]
	global_load_dwordx4 v[28:31], v8, s[96:97]
	global_load_dwordx4 v[32:35], v9, s[96:97]
	global_load_dwordx4 v[36:39], v10, s[96:97]
	global_load_dwordx4 v[40:43], v11, s[96:97]
	global_load_dwordx4 v[44:47], v12, s[96:97]
	global_load_dwordx4 v[48:51], v13, s[96:97]
	ds_read2_b32 v[52:53], v15 offset0:0 offset1:33
	ds_read2_b32 v[54:55], v15 offset0:66 offset1:99
	ds_read2_b32 v[56:57], v15 offset0:132 offset1:165
	ds_read2_b32 v[58:59], v15 offset0:198 offset1:231
	ds_read2_b32 v[60:61], v15 offset0:8 offset1:41
	ds_read2_b32 v[62:63], v15 offset0:74 offset1:107
	ds_read2_b32 v[64:65], v15 offset0:140 offset1:173
	ds_read2_b32 v[66:67], v15 offset0:206 offset1:239
	ds_read2_b32 v[68:69], v15 offset0:16 offset1:49
	ds_read2_b32 v[70:71], v15 offset0:82 offset1:115
	ds_read2_b32 v[72:73], v15 offset0:148 offset1:181
	ds_read2_b32 v[74:75], v15 offset0:214 offset1:247
	ds_read2_b32 v[76:77], v15 offset0:24 offset1:57
	ds_read2_b32 v[78:79], v15 offset0:90 offset1:123
	ds_read2_b32 v[80:81], v15 offset0:156 offset1:189
	ds_read2_b32 v[82:83], v15 offset0:222 offset1:255
	s_add_u32 s95, s94, 0x1000
	s_lshr_b32 vcc_lo, s95, 7
	s_and_b32 vcc_hi, s95, 0x7f
	s_mul_i32 vcc_hi, vcc_hi, 0xac000
	s_lshl_b32 vcc_lo, vcc_lo, 7
	s_add_u32 s98, s66, 0x12d00000
	s_addc_u32 s99, s67, 0
	s_add_u32 s98, s98, vcc_hi
	s_addc_u32 s99, s99, 0
	s_add_u32 s98, s98, vcc_lo
	s_addc_u32 s99, s99, 0
	s_waitcnt lgkmcnt(0)
	v_cvt_pk_bf16_f32 v84, v52, v53
	v_cvt_pk_bf16_f32 v85, v54, v55
	v_cvt_pk_bf16_f32 v86, v56, v57
	v_cvt_pk_bf16_f32 v87, v58, v59
	v_cvt_pk_bf16_f32 v88, v60, v61
	v_cvt_pk_bf16_f32 v89, v62, v63
	v_cvt_pk_bf16_f32 v90, v64, v65
	v_cvt_pk_bf16_f32 v91, v66, v67
	v_cvt_pk_bf16_f32 v92, v68, v69
	v_cvt_pk_bf16_f32 v93, v70, v71
	v_cvt_pk_bf16_f32 v94, v72, v73
	v_cvt_pk_bf16_f32 v95, v74, v75
	v_cvt_pk_bf16_f32 v96, v76, v77
	v_cvt_pk_bf16_f32 v97, v78, v79
	v_cvt_pk_bf16_f32 v98, v80, v81
	v_cvt_pk_bf16_f32 v99, v82, v83
	global_store_dwordx4 v16, v[84:87], s[98:99]
	global_store_dwordx4 v17, v[88:91], s[98:99]
	global_store_dwordx4 v18, v[92:95], s[98:99]
	global_store_dwordx4 v19, v[96:99], s[98:99]
	s_waitcnt vmcnt(23)
	ds_write_b32 v14, v100 offset:0
	ds_write_b32 v14, v101 offset:4
	ds_write_b32 v14, v102 offset:8
	ds_write_b32 v14, v103 offset:12
	s_waitcnt vmcnt(22)
	ds_write_b32 v14, v104 offset:1056
	ds_write_b32 v14, v105 offset:1060
	ds_write_b32 v14, v106 offset:1064
	ds_write_b32 v14, v107 offset:1068
	s_waitcnt vmcnt(21)
	ds_write_b32 v14, v108 offset:2112
	ds_write_b32 v14, v109 offset:2116
	ds_write_b32 v14, v110 offset:2120
	ds_write_b32 v14, v111 offset:2124
	s_waitcnt vmcnt(20)
	ds_write_b32 v14, v112 offset:3168
	ds_write_b32 v14, v113 offset:3172
	ds_write_b32 v14, v114 offset:3176
	ds_write_b32 v14, v115 offset:3180
	s_waitcnt vmcnt(19)
	ds_write_b32 v14, v116 offset:4224
	ds_write_b32 v14, v117 offset:4228
	ds_write_b32 v14, v118 offset:4232
	ds_write_b32 v14, v119 offset:4236
	s_waitcnt vmcnt(18)
	ds_write_b32 v14, v120 offset:5280
	ds_write_b32 v14, v121 offset:5284
	ds_write_b32 v14, v122 offset:5288
	ds_write_b32 v14, v123 offset:5292
	s_waitcnt vmcnt(17)
	ds_write_b32 v14, v124 offset:6336
	ds_write_b32 v14, v125 offset:6340
	ds_write_b32 v14, v126 offset:6344
	ds_write_b32 v14, v127 offset:6348
	s_waitcnt vmcnt(16)
	ds_write_b32 v14, v128 offset:7392
	ds_write_b32 v14, v129 offset:7396
	ds_write_b32 v14, v130 offset:7400
	ds_write_b32 v14, v131 offset:7404
	s_add_u32 s95, s94, 0x1c00
	s_lshr_b32 vcc_lo, s95, 7
	s_and_b32 vcc_hi, s95, 0x7f
	s_lshl_b32 vcc_lo, vcc_lo, 20
	s_lshl_b32 vcc_hi, vcc_hi, 7
	s_add_u32 s96, s100, vcc_lo
	s_addc_u32 s97, s101, 0
	s_add_u32 s96, s96, vcc_hi
	s_addc_u32 s97, s97, 0
	global_load_dwordx4 v[100:103], v6, s[96:97]
	global_load_dwordx4 v[104:107], v7, s[96:97]
	global_load_dwordx4 v[108:111], v8, s[96:97]
	global_load_dwordx4 v[112:115], v9, s[96:97]
	global_load_dwordx4 v[116:119], v10, s[96:97]
	global_load_dwordx4 v[120:123], v11, s[96:97]
	global_load_dwordx4 v[124:127], v12, s[96:97]
	global_load_dwordx4 v[128:131], v13, s[96:97]
	ds_read2_b32 v[52:53], v15 offset0:0 offset1:33
	ds_read2_b32 v[54:55], v15 offset0:66 offset1:99
	ds_read2_b32 v[56:57], v15 offset0:132 offset1:165
	ds_read2_b32 v[58:59], v15 offset0:198 offset1:231
	ds_read2_b32 v[60:61], v15 offset0:8 offset1:41
	ds_read2_b32 v[62:63], v15 offset0:74 offset1:107
	ds_read2_b32 v[64:65], v15 offset0:140 offset1:173
	ds_read2_b32 v[66:67], v15 offset0:206 offset1:239
	ds_read2_b32 v[68:69], v15 offset0:16 offset1:49
	ds_read2_b32 v[70:71], v15 offset0:82 offset1:115
	ds_read2_b32 v[72:73], v15 offset0:148 offset1:181
	ds_read2_b32 v[74:75], v15 offset0:214 offset1:247
	ds_read2_b32 v[76:77], v15 offset0:24 offset1:57
	ds_read2_b32 v[78:79], v15 offset0:90 offset1:123
	ds_read2_b32 v[80:81], v15 offset0:156 offset1:189
	ds_read2_b32 v[82:83], v15 offset0:222 offset1:255
	s_add_u32 s95, s94, 0x1400
	s_lshr_b32 vcc_lo, s95, 7
	s_and_b32 vcc_hi, s95, 0x7f
	s_mul_i32 vcc_hi, vcc_hi, 0xac000
	s_lshl_b32 vcc_lo, vcc_lo, 7
	s_add_u32 s98, s66, 0x12d00000
	s_addc_u32 s99, s67, 0
	s_add_u32 s98, s98, vcc_hi
	s_addc_u32 s99, s99, 0
	s_add_u32 s98, s98, vcc_lo
	s_addc_u32 s99, s99, 0
	s_waitcnt lgkmcnt(0)
	v_cvt_pk_bf16_f32 v84, v52, v53
	v_cvt_pk_bf16_f32 v85, v54, v55
	v_cvt_pk_bf16_f32 v86, v56, v57
	v_cvt_pk_bf16_f32 v87, v58, v59
	v_cvt_pk_bf16_f32 v88, v60, v61
	v_cvt_pk_bf16_f32 v89, v62, v63
	v_cvt_pk_bf16_f32 v90, v64, v65
	v_cvt_pk_bf16_f32 v91, v66, v67
	v_cvt_pk_bf16_f32 v92, v68, v69
	v_cvt_pk_bf16_f32 v93, v70, v71
	v_cvt_pk_bf16_f32 v94, v72, v73
	v_cvt_pk_bf16_f32 v95, v74, v75
	v_cvt_pk_bf16_f32 v96, v76, v77
	v_cvt_pk_bf16_f32 v97, v78, v79
	v_cvt_pk_bf16_f32 v98, v80, v81
	v_cvt_pk_bf16_f32 v99, v82, v83
	global_store_dwordx4 v16, v[84:87], s[98:99]
	global_store_dwordx4 v17, v[88:91], s[98:99]
	global_store_dwordx4 v18, v[92:95], s[98:99]
	global_store_dwordx4 v19, v[96:99], s[98:99]
	s_waitcnt vmcnt(23)
	ds_write_b32 v14, v20 offset:0
	ds_write_b32 v14, v21 offset:4
	ds_write_b32 v14, v22 offset:8
	ds_write_b32 v14, v23 offset:12
	s_waitcnt vmcnt(22)
	ds_write_b32 v14, v24 offset:1056
	ds_write_b32 v14, v25 offset:1060
	ds_write_b32 v14, v26 offset:1064
	ds_write_b32 v14, v27 offset:1068
	s_waitcnt vmcnt(21)
	ds_write_b32 v14, v28 offset:2112
	ds_write_b32 v14, v29 offset:2116
	ds_write_b32 v14, v30 offset:2120
	ds_write_b32 v14, v31 offset:2124
	s_waitcnt vmcnt(20)
	ds_write_b32 v14, v32 offset:3168
	ds_write_b32 v14, v33 offset:3172
	ds_write_b32 v14, v34 offset:3176
	ds_write_b32 v14, v35 offset:3180
	s_waitcnt vmcnt(19)
	ds_write_b32 v14, v36 offset:4224
	ds_write_b32 v14, v37 offset:4228
	ds_write_b32 v14, v38 offset:4232
	ds_write_b32 v14, v39 offset:4236
	s_waitcnt vmcnt(18)
	ds_write_b32 v14, v40 offset:5280
	ds_write_b32 v14, v41 offset:5284
	ds_write_b32 v14, v42 offset:5288
	ds_write_b32 v14, v43 offset:5292
	s_waitcnt vmcnt(17)
	ds_write_b32 v14, v44 offset:6336
	ds_write_b32 v14, v45 offset:6340
	ds_write_b32 v14, v46 offset:6344
	ds_write_b32 v14, v47 offset:6348
	s_waitcnt vmcnt(16)
	ds_write_b32 v14, v48 offset:7392
	ds_write_b32 v14, v49 offset:7396
	ds_write_b32 v14, v50 offset:7400
	ds_write_b32 v14, v51 offset:7404
	s_add_u32 s95, s94, 0x2000
	s_lshr_b32 vcc_lo, s95, 7
	s_and_b32 vcc_hi, s95, 0x7f
	s_lshl_b32 vcc_lo, vcc_lo, 20
	s_lshl_b32 vcc_hi, vcc_hi, 7
	s_add_u32 s96, s100, vcc_lo
	s_addc_u32 s97, s101, 0
	s_add_u32 s96, s96, vcc_hi
	s_addc_u32 s97, s97, 0
	global_load_dwordx4 v[20:23], v6, s[96:97]
	global_load_dwordx4 v[24:27], v7, s[96:97]
	global_load_dwordx4 v[28:31], v8, s[96:97]
	global_load_dwordx4 v[32:35], v9, s[96:97]
	global_load_dwordx4 v[36:39], v10, s[96:97]
	global_load_dwordx4 v[40:43], v11, s[96:97]
	global_load_dwordx4 v[44:47], v12, s[96:97]
	global_load_dwordx4 v[48:51], v13, s[96:97]
	ds_read2_b32 v[52:53], v15 offset0:0 offset1:33
	ds_read2_b32 v[54:55], v15 offset0:66 offset1:99
	ds_read2_b32 v[56:57], v15 offset0:132 offset1:165
	ds_read2_b32 v[58:59], v15 offset0:198 offset1:231
	ds_read2_b32 v[60:61], v15 offset0:8 offset1:41
	ds_read2_b32 v[62:63], v15 offset0:74 offset1:107
	ds_read2_b32 v[64:65], v15 offset0:140 offset1:173
	ds_read2_b32 v[66:67], v15 offset0:206 offset1:239
	ds_read2_b32 v[68:69], v15 offset0:16 offset1:49
	ds_read2_b32 v[70:71], v15 offset0:82 offset1:115
	ds_read2_b32 v[72:73], v15 offset0:148 offset1:181
	ds_read2_b32 v[74:75], v15 offset0:214 offset1:247
	ds_read2_b32 v[76:77], v15 offset0:24 offset1:57
	ds_read2_b32 v[78:79], v15 offset0:90 offset1:123
	ds_read2_b32 v[80:81], v15 offset0:156 offset1:189
	ds_read2_b32 v[82:83], v15 offset0:222 offset1:255
	s_add_u32 s95, s94, 0x1800
	s_lshr_b32 vcc_lo, s95, 7
	s_and_b32 vcc_hi, s95, 0x7f
	s_mul_i32 vcc_hi, vcc_hi, 0xac000
	s_lshl_b32 vcc_lo, vcc_lo, 7
	s_add_u32 s98, s66, 0x12d00000
	s_addc_u32 s99, s67, 0
	s_add_u32 s98, s98, vcc_hi
	s_addc_u32 s99, s99, 0
	s_add_u32 s98, s98, vcc_lo
	s_addc_u32 s99, s99, 0
	s_waitcnt lgkmcnt(0)
	v_cvt_pk_bf16_f32 v84, v52, v53
	v_cvt_pk_bf16_f32 v85, v54, v55
	v_cvt_pk_bf16_f32 v86, v56, v57
	v_cvt_pk_bf16_f32 v87, v58, v59
	v_cvt_pk_bf16_f32 v88, v60, v61
	v_cvt_pk_bf16_f32 v89, v62, v63
	v_cvt_pk_bf16_f32 v90, v64, v65
	v_cvt_pk_bf16_f32 v91, v66, v67
	v_cvt_pk_bf16_f32 v92, v68, v69
	v_cvt_pk_bf16_f32 v93, v70, v71
	v_cvt_pk_bf16_f32 v94, v72, v73
	v_cvt_pk_bf16_f32 v95, v74, v75
	v_cvt_pk_bf16_f32 v96, v76, v77
	v_cvt_pk_bf16_f32 v97, v78, v79
	v_cvt_pk_bf16_f32 v98, v80, v81
	v_cvt_pk_bf16_f32 v99, v82, v83
	global_store_dwordx4 v16, v[84:87], s[98:99]
	global_store_dwordx4 v17, v[88:91], s[98:99]
	global_store_dwordx4 v18, v[92:95], s[98:99]
	global_store_dwordx4 v19, v[96:99], s[98:99]
	s_waitcnt vmcnt(23)
	ds_write_b32 v14, v100 offset:0
	ds_write_b32 v14, v101 offset:4
	ds_write_b32 v14, v102 offset:8
	ds_write_b32 v14, v103 offset:12
	s_waitcnt vmcnt(22)
	ds_write_b32 v14, v104 offset:1056
	ds_write_b32 v14, v105 offset:1060
	ds_write_b32 v14, v106 offset:1064
	ds_write_b32 v14, v107 offset:1068
	s_waitcnt vmcnt(21)
	ds_write_b32 v14, v108 offset:2112
	ds_write_b32 v14, v109 offset:2116
	ds_write_b32 v14, v110 offset:2120
	ds_write_b32 v14, v111 offset:2124
	s_waitcnt vmcnt(20)
	ds_write_b32 v14, v112 offset:3168
	ds_write_b32 v14, v113 offset:3172
	ds_write_b32 v14, v114 offset:3176
	ds_write_b32 v14, v115 offset:3180
	s_waitcnt vmcnt(19)
	ds_write_b32 v14, v116 offset:4224
	ds_write_b32 v14, v117 offset:4228
	ds_write_b32 v14, v118 offset:4232
	ds_write_b32 v14, v119 offset:4236
	s_waitcnt vmcnt(18)
	ds_write_b32 v14, v120 offset:5280
	ds_write_b32 v14, v121 offset:5284
	ds_write_b32 v14, v122 offset:5288
	ds_write_b32 v14, v123 offset:5292
	s_waitcnt vmcnt(17)
	ds_write_b32 v14, v124 offset:6336
	ds_write_b32 v14, v125 offset:6340
	ds_write_b32 v14, v126 offset:6344
	ds_write_b32 v14, v127 offset:6348
	s_waitcnt vmcnt(16)
	ds_write_b32 v14, v128 offset:7392
	ds_write_b32 v14, v129 offset:7396
	ds_write_b32 v14, v130 offset:7400
	ds_write_b32 v14, v131 offset:7404
	s_add_u32 s95, s94, 0x2400
	s_lshr_b32 vcc_lo, s95, 7
	s_and_b32 vcc_hi, s95, 0x7f
	s_lshl_b32 vcc_lo, vcc_lo, 20
	s_lshl_b32 vcc_hi, vcc_hi, 7
	s_add_u32 s96, s100, vcc_lo
	s_addc_u32 s97, s101, 0
	s_add_u32 s96, s96, vcc_hi
	s_addc_u32 s97, s97, 0
	global_load_dwordx4 v[100:103], v6, s[96:97]
	global_load_dwordx4 v[104:107], v7, s[96:97]
	global_load_dwordx4 v[108:111], v8, s[96:97]
	global_load_dwordx4 v[112:115], v9, s[96:97]
	global_load_dwordx4 v[116:119], v10, s[96:97]
	global_load_dwordx4 v[120:123], v11, s[96:97]
	global_load_dwordx4 v[124:127], v12, s[96:97]
	global_load_dwordx4 v[128:131], v13, s[96:97]
	ds_read2_b32 v[52:53], v15 offset0:0 offset1:33
	ds_read2_b32 v[54:55], v15 offset0:66 offset1:99
	ds_read2_b32 v[56:57], v15 offset0:132 offset1:165
	ds_read2_b32 v[58:59], v15 offset0:198 offset1:231
	ds_read2_b32 v[60:61], v15 offset0:8 offset1:41
	ds_read2_b32 v[62:63], v15 offset0:74 offset1:107
	ds_read2_b32 v[64:65], v15 offset0:140 offset1:173
	ds_read2_b32 v[66:67], v15 offset0:206 offset1:239
	ds_read2_b32 v[68:69], v15 offset0:16 offset1:49
	ds_read2_b32 v[70:71], v15 offset0:82 offset1:115
	ds_read2_b32 v[72:73], v15 offset0:148 offset1:181
	ds_read2_b32 v[74:75], v15 offset0:214 offset1:247
	ds_read2_b32 v[76:77], v15 offset0:24 offset1:57
	ds_read2_b32 v[78:79], v15 offset0:90 offset1:123
	ds_read2_b32 v[80:81], v15 offset0:156 offset1:189
	ds_read2_b32 v[82:83], v15 offset0:222 offset1:255
	s_add_u32 s95, s94, 0x1c00
	s_lshr_b32 vcc_lo, s95, 7
	s_and_b32 vcc_hi, s95, 0x7f
	s_mul_i32 vcc_hi, vcc_hi, 0xac000
	s_lshl_b32 vcc_lo, vcc_lo, 7
	s_add_u32 s98, s66, 0x12d00000
	s_addc_u32 s99, s67, 0
	s_add_u32 s98, s98, vcc_hi
	s_addc_u32 s99, s99, 0
	s_add_u32 s98, s98, vcc_lo
	s_addc_u32 s99, s99, 0
	s_waitcnt lgkmcnt(0)
	v_cvt_pk_bf16_f32 v84, v52, v53
	v_cvt_pk_bf16_f32 v85, v54, v55
	v_cvt_pk_bf16_f32 v86, v56, v57
	v_cvt_pk_bf16_f32 v87, v58, v59
	v_cvt_pk_bf16_f32 v88, v60, v61
	v_cvt_pk_bf16_f32 v89, v62, v63
	v_cvt_pk_bf16_f32 v90, v64, v65
	v_cvt_pk_bf16_f32 v91, v66, v67
	v_cvt_pk_bf16_f32 v92, v68, v69
	v_cvt_pk_bf16_f32 v93, v70, v71
	v_cvt_pk_bf16_f32 v94, v72, v73
	v_cvt_pk_bf16_f32 v95, v74, v75
	v_cvt_pk_bf16_f32 v96, v76, v77
	v_cvt_pk_bf16_f32 v97, v78, v79
	v_cvt_pk_bf16_f32 v98, v80, v81
	v_cvt_pk_bf16_f32 v99, v82, v83
	global_store_dwordx4 v16, v[84:87], s[98:99]
	global_store_dwordx4 v17, v[88:91], s[98:99]
	global_store_dwordx4 v18, v[92:95], s[98:99]
	global_store_dwordx4 v19, v[96:99], s[98:99]
	s_waitcnt vmcnt(23)
	ds_write_b32 v14, v20 offset:0
	ds_write_b32 v14, v21 offset:4
	ds_write_b32 v14, v22 offset:8
	ds_write_b32 v14, v23 offset:12
	s_waitcnt vmcnt(22)
	ds_write_b32 v14, v24 offset:1056
	ds_write_b32 v14, v25 offset:1060
	ds_write_b32 v14, v26 offset:1064
	ds_write_b32 v14, v27 offset:1068
	s_waitcnt vmcnt(21)
	ds_write_b32 v14, v28 offset:2112
	ds_write_b32 v14, v29 offset:2116
	ds_write_b32 v14, v30 offset:2120
	ds_write_b32 v14, v31 offset:2124
	s_waitcnt vmcnt(20)
	ds_write_b32 v14, v32 offset:3168
	ds_write_b32 v14, v33 offset:3172
	ds_write_b32 v14, v34 offset:3176
	ds_write_b32 v14, v35 offset:3180
	s_waitcnt vmcnt(19)
	ds_write_b32 v14, v36 offset:4224
	ds_write_b32 v14, v37 offset:4228
	ds_write_b32 v14, v38 offset:4232
	ds_write_b32 v14, v39 offset:4236
	s_waitcnt vmcnt(18)
	ds_write_b32 v14, v40 offset:5280
	ds_write_b32 v14, v41 offset:5284
	ds_write_b32 v14, v42 offset:5288
	ds_write_b32 v14, v43 offset:5292
	s_waitcnt vmcnt(17)
	ds_write_b32 v14, v44 offset:6336
	ds_write_b32 v14, v45 offset:6340
	ds_write_b32 v14, v46 offset:6344
	ds_write_b32 v14, v47 offset:6348
	s_waitcnt vmcnt(16)
	ds_write_b32 v14, v48 offset:7392
	ds_write_b32 v14, v49 offset:7396
	ds_write_b32 v14, v50 offset:7400
	ds_write_b32 v14, v51 offset:7404
	s_add_u32 s95, s94, 0x2800
	s_lshr_b32 vcc_lo, s95, 7
	s_and_b32 vcc_hi, s95, 0x7f
	s_lshl_b32 vcc_lo, vcc_lo, 20
	s_lshl_b32 vcc_hi, vcc_hi, 7
	s_add_u32 s96, s100, vcc_lo
	s_addc_u32 s97, s101, 0
	s_add_u32 s96, s96, vcc_hi
	s_addc_u32 s97, s97, 0
	global_load_dwordx4 v[20:23], v6, s[96:97]
	global_load_dwordx4 v[24:27], v7, s[96:97]
	global_load_dwordx4 v[28:31], v8, s[96:97]
	global_load_dwordx4 v[32:35], v9, s[96:97]
	global_load_dwordx4 v[36:39], v10, s[96:97]
	global_load_dwordx4 v[40:43], v11, s[96:97]
	global_load_dwordx4 v[44:47], v12, s[96:97]
	global_load_dwordx4 v[48:51], v13, s[96:97]
	ds_read2_b32 v[52:53], v15 offset0:0 offset1:33
	ds_read2_b32 v[54:55], v15 offset0:66 offset1:99
	ds_read2_b32 v[56:57], v15 offset0:132 offset1:165
	ds_read2_b32 v[58:59], v15 offset0:198 offset1:231
	ds_read2_b32 v[60:61], v15 offset0:8 offset1:41
	ds_read2_b32 v[62:63], v15 offset0:74 offset1:107
	ds_read2_b32 v[64:65], v15 offset0:140 offset1:173
	ds_read2_b32 v[66:67], v15 offset0:206 offset1:239
	ds_read2_b32 v[68:69], v15 offset0:16 offset1:49
	ds_read2_b32 v[70:71], v15 offset0:82 offset1:115
	ds_read2_b32 v[72:73], v15 offset0:148 offset1:181
	ds_read2_b32 v[74:75], v15 offset0:214 offset1:247
	ds_read2_b32 v[76:77], v15 offset0:24 offset1:57
	ds_read2_b32 v[78:79], v15 offset0:90 offset1:123
	ds_read2_b32 v[80:81], v15 offset0:156 offset1:189
	ds_read2_b32 v[82:83], v15 offset0:222 offset1:255
	s_add_u32 s95, s94, 0x2000
	s_lshr_b32 vcc_lo, s95, 7
	s_and_b32 vcc_hi, s95, 0x7f
	s_mul_i32 vcc_hi, vcc_hi, 0xac000
	s_lshl_b32 vcc_lo, vcc_lo, 7
	s_add_u32 s98, s66, 0x12d00000
	s_addc_u32 s99, s67, 0
	s_add_u32 s98, s98, vcc_hi
	s_addc_u32 s99, s99, 0
	s_add_u32 s98, s98, vcc_lo
	s_addc_u32 s99, s99, 0
	s_waitcnt lgkmcnt(0)
	v_cvt_pk_bf16_f32 v84, v52, v53
	v_cvt_pk_bf16_f32 v85, v54, v55
	v_cvt_pk_bf16_f32 v86, v56, v57
	v_cvt_pk_bf16_f32 v87, v58, v59
	v_cvt_pk_bf16_f32 v88, v60, v61
	v_cvt_pk_bf16_f32 v89, v62, v63
	v_cvt_pk_bf16_f32 v90, v64, v65
	v_cvt_pk_bf16_f32 v91, v66, v67
	v_cvt_pk_bf16_f32 v92, v68, v69
	v_cvt_pk_bf16_f32 v93, v70, v71
	v_cvt_pk_bf16_f32 v94, v72, v73
	v_cvt_pk_bf16_f32 v95, v74, v75
	v_cvt_pk_bf16_f32 v96, v76, v77
	v_cvt_pk_bf16_f32 v97, v78, v79
	v_cvt_pk_bf16_f32 v98, v80, v81
	v_cvt_pk_bf16_f32 v99, v82, v83
	global_store_dwordx4 v16, v[84:87], s[98:99]
	global_store_dwordx4 v17, v[88:91], s[98:99]
	global_store_dwordx4 v18, v[92:95], s[98:99]
	global_store_dwordx4 v19, v[96:99], s[98:99]
	s_waitcnt vmcnt(23)
	ds_write_b32 v14, v100 offset:0
	ds_write_b32 v14, v101 offset:4
	ds_write_b32 v14, v102 offset:8
	ds_write_b32 v14, v103 offset:12
	s_waitcnt vmcnt(22)
	ds_write_b32 v14, v104 offset:1056
	ds_write_b32 v14, v105 offset:1060
	ds_write_b32 v14, v106 offset:1064
	ds_write_b32 v14, v107 offset:1068
	s_waitcnt vmcnt(21)
	ds_write_b32 v14, v108 offset:2112
	ds_write_b32 v14, v109 offset:2116
	ds_write_b32 v14, v110 offset:2120
	ds_write_b32 v14, v111 offset:2124
	s_waitcnt vmcnt(20)
	ds_write_b32 v14, v112 offset:3168
	ds_write_b32 v14, v113 offset:3172
	ds_write_b32 v14, v114 offset:3176
	ds_write_b32 v14, v115 offset:3180
	s_waitcnt vmcnt(19)
	ds_write_b32 v14, v116 offset:4224
	ds_write_b32 v14, v117 offset:4228
	ds_write_b32 v14, v118 offset:4232
	ds_write_b32 v14, v119 offset:4236
	s_waitcnt vmcnt(18)
	ds_write_b32 v14, v120 offset:5280
	ds_write_b32 v14, v121 offset:5284
	ds_write_b32 v14, v122 offset:5288
	ds_write_b32 v14, v123 offset:5292
	s_waitcnt vmcnt(17)
	ds_write_b32 v14, v124 offset:6336
	ds_write_b32 v14, v125 offset:6340
	ds_write_b32 v14, v126 offset:6344
	ds_write_b32 v14, v127 offset:6348
	s_waitcnt vmcnt(16)
	ds_write_b32 v14, v128 offset:7392
	ds_write_b32 v14, v129 offset:7396
	ds_write_b32 v14, v130 offset:7400
	ds_write_b32 v14, v131 offset:7404
	s_add_u32 s95, s94, 0x2c00
	s_lshr_b32 vcc_lo, s95, 7
	s_and_b32 vcc_hi, s95, 0x7f
	s_lshl_b32 vcc_lo, vcc_lo, 20
	s_lshl_b32 vcc_hi, vcc_hi, 7
	s_add_u32 s96, s100, vcc_lo
	s_addc_u32 s97, s101, 0
	s_add_u32 s96, s96, vcc_hi
	s_addc_u32 s97, s97, 0
	global_load_dwordx4 v[100:103], v6, s[96:97]
	global_load_dwordx4 v[104:107], v7, s[96:97]
	global_load_dwordx4 v[108:111], v8, s[96:97]
	global_load_dwordx4 v[112:115], v9, s[96:97]
	global_load_dwordx4 v[116:119], v10, s[96:97]
	global_load_dwordx4 v[120:123], v11, s[96:97]
	global_load_dwordx4 v[124:127], v12, s[96:97]
	global_load_dwordx4 v[128:131], v13, s[96:97]
	ds_read2_b32 v[52:53], v15 offset0:0 offset1:33
	ds_read2_b32 v[54:55], v15 offset0:66 offset1:99
	ds_read2_b32 v[56:57], v15 offset0:132 offset1:165
	ds_read2_b32 v[58:59], v15 offset0:198 offset1:231
	ds_read2_b32 v[60:61], v15 offset0:8 offset1:41
	ds_read2_b32 v[62:63], v15 offset0:74 offset1:107
	ds_read2_b32 v[64:65], v15 offset0:140 offset1:173
	ds_read2_b32 v[66:67], v15 offset0:206 offset1:239
	ds_read2_b32 v[68:69], v15 offset0:16 offset1:49
	ds_read2_b32 v[70:71], v15 offset0:82 offset1:115
	ds_read2_b32 v[72:73], v15 offset0:148 offset1:181
	ds_read2_b32 v[74:75], v15 offset0:214 offset1:247
	ds_read2_b32 v[76:77], v15 offset0:24 offset1:57
	ds_read2_b32 v[78:79], v15 offset0:90 offset1:123
	ds_read2_b32 v[80:81], v15 offset0:156 offset1:189
	ds_read2_b32 v[82:83], v15 offset0:222 offset1:255
	s_add_u32 s95, s94, 0x2400
	s_lshr_b32 vcc_lo, s95, 7
	s_and_b32 vcc_hi, s95, 0x7f
	s_mul_i32 vcc_hi, vcc_hi, 0xac000
	s_lshl_b32 vcc_lo, vcc_lo, 7
	s_add_u32 s98, s66, 0x12d00000
	s_addc_u32 s99, s67, 0
	s_add_u32 s98, s98, vcc_hi
	s_addc_u32 s99, s99, 0
	s_add_u32 s98, s98, vcc_lo
	s_addc_u32 s99, s99, 0
	s_waitcnt lgkmcnt(0)
	v_cvt_pk_bf16_f32 v84, v52, v53
	v_cvt_pk_bf16_f32 v85, v54, v55
	v_cvt_pk_bf16_f32 v86, v56, v57
	v_cvt_pk_bf16_f32 v87, v58, v59
	v_cvt_pk_bf16_f32 v88, v60, v61
	v_cvt_pk_bf16_f32 v89, v62, v63
	v_cvt_pk_bf16_f32 v90, v64, v65
	v_cvt_pk_bf16_f32 v91, v66, v67
	v_cvt_pk_bf16_f32 v92, v68, v69
	v_cvt_pk_bf16_f32 v93, v70, v71
	v_cvt_pk_bf16_f32 v94, v72, v73
	v_cvt_pk_bf16_f32 v95, v74, v75
	v_cvt_pk_bf16_f32 v96, v76, v77
	v_cvt_pk_bf16_f32 v97, v78, v79
	v_cvt_pk_bf16_f32 v98, v80, v81
	v_cvt_pk_bf16_f32 v99, v82, v83
	global_store_dwordx4 v16, v[84:87], s[98:99]
	global_store_dwordx4 v17, v[88:91], s[98:99]
	global_store_dwordx4 v18, v[92:95], s[98:99]
	global_store_dwordx4 v19, v[96:99], s[98:99]
	s_waitcnt vmcnt(23)
	ds_write_b32 v14, v20 offset:0
	ds_write_b32 v14, v21 offset:4
	ds_write_b32 v14, v22 offset:8
	ds_write_b32 v14, v23 offset:12
	s_waitcnt vmcnt(22)
	ds_write_b32 v14, v24 offset:1056
	ds_write_b32 v14, v25 offset:1060
	ds_write_b32 v14, v26 offset:1064
	ds_write_b32 v14, v27 offset:1068
	s_waitcnt vmcnt(21)
	ds_write_b32 v14, v28 offset:2112
	ds_write_b32 v14, v29 offset:2116
	ds_write_b32 v14, v30 offset:2120
	ds_write_b32 v14, v31 offset:2124
	s_waitcnt vmcnt(20)
	ds_write_b32 v14, v32 offset:3168
	ds_write_b32 v14, v33 offset:3172
	ds_write_b32 v14, v34 offset:3176
	ds_write_b32 v14, v35 offset:3180
	s_waitcnt vmcnt(19)
	ds_write_b32 v14, v36 offset:4224
	ds_write_b32 v14, v37 offset:4228
	ds_write_b32 v14, v38 offset:4232
	ds_write_b32 v14, v39 offset:4236
	s_waitcnt vmcnt(18)
	ds_write_b32 v14, v40 offset:5280
	ds_write_b32 v14, v41 offset:5284
	ds_write_b32 v14, v42 offset:5288
	ds_write_b32 v14, v43 offset:5292
	s_waitcnt vmcnt(17)
	ds_write_b32 v14, v44 offset:6336
	ds_write_b32 v14, v45 offset:6340
	ds_write_b32 v14, v46 offset:6344
	ds_write_b32 v14, v47 offset:6348
	s_waitcnt vmcnt(16)
	ds_write_b32 v14, v48 offset:7392
	ds_write_b32 v14, v49 offset:7396
	ds_write_b32 v14, v50 offset:7400
	ds_write_b32 v14, v51 offset:7404
	s_add_u32 s95, s94, 0x3000
	s_lshr_b32 vcc_lo, s95, 7
	s_and_b32 vcc_hi, s95, 0x7f
	s_lshl_b32 vcc_lo, vcc_lo, 20
	s_lshl_b32 vcc_hi, vcc_hi, 7
	s_add_u32 s96, s100, vcc_lo
	s_addc_u32 s97, s101, 0
	s_add_u32 s96, s96, vcc_hi
	s_addc_u32 s97, s97, 0
	global_load_dwordx4 v[20:23], v6, s[96:97]
	global_load_dwordx4 v[24:27], v7, s[96:97]
	global_load_dwordx4 v[28:31], v8, s[96:97]
	global_load_dwordx4 v[32:35], v9, s[96:97]
	global_load_dwordx4 v[36:39], v10, s[96:97]
	global_load_dwordx4 v[40:43], v11, s[96:97]
	global_load_dwordx4 v[44:47], v12, s[96:97]
	global_load_dwordx4 v[48:51], v13, s[96:97]
	ds_read2_b32 v[52:53], v15 offset0:0 offset1:33
	ds_read2_b32 v[54:55], v15 offset0:66 offset1:99
	ds_read2_b32 v[56:57], v15 offset0:132 offset1:165
	ds_read2_b32 v[58:59], v15 offset0:198 offset1:231
	ds_read2_b32 v[60:61], v15 offset0:8 offset1:41
	ds_read2_b32 v[62:63], v15 offset0:74 offset1:107
	ds_read2_b32 v[64:65], v15 offset0:140 offset1:173
	ds_read2_b32 v[66:67], v15 offset0:206 offset1:239
	ds_read2_b32 v[68:69], v15 offset0:16 offset1:49
	ds_read2_b32 v[70:71], v15 offset0:82 offset1:115
	ds_read2_b32 v[72:73], v15 offset0:148 offset1:181
	ds_read2_b32 v[74:75], v15 offset0:214 offset1:247
	ds_read2_b32 v[76:77], v15 offset0:24 offset1:57
	ds_read2_b32 v[78:79], v15 offset0:90 offset1:123
	ds_read2_b32 v[80:81], v15 offset0:156 offset1:189
	ds_read2_b32 v[82:83], v15 offset0:222 offset1:255
	s_add_u32 s95, s94, 0x2800
	s_lshr_b32 vcc_lo, s95, 7
	s_and_b32 vcc_hi, s95, 0x7f
	s_mul_i32 vcc_hi, vcc_hi, 0xac000
	s_lshl_b32 vcc_lo, vcc_lo, 7
	s_add_u32 s98, s66, 0x12d00000
	s_addc_u32 s99, s67, 0
	s_add_u32 s98, s98, vcc_hi
	s_addc_u32 s99, s99, 0
	s_add_u32 s98, s98, vcc_lo
	s_addc_u32 s99, s99, 0
	s_waitcnt lgkmcnt(0)
	v_cvt_pk_bf16_f32 v84, v52, v53
	v_cvt_pk_bf16_f32 v85, v54, v55
	v_cvt_pk_bf16_f32 v86, v56, v57
	v_cvt_pk_bf16_f32 v87, v58, v59
	v_cvt_pk_bf16_f32 v88, v60, v61
	v_cvt_pk_bf16_f32 v89, v62, v63
	v_cvt_pk_bf16_f32 v90, v64, v65
	v_cvt_pk_bf16_f32 v91, v66, v67
	v_cvt_pk_bf16_f32 v92, v68, v69
	v_cvt_pk_bf16_f32 v93, v70, v71
	v_cvt_pk_bf16_f32 v94, v72, v73
	v_cvt_pk_bf16_f32 v95, v74, v75
	v_cvt_pk_bf16_f32 v96, v76, v77
	v_cvt_pk_bf16_f32 v97, v78, v79
	v_cvt_pk_bf16_f32 v98, v80, v81
	v_cvt_pk_bf16_f32 v99, v82, v83
	global_store_dwordx4 v16, v[84:87], s[98:99]
	global_store_dwordx4 v17, v[88:91], s[98:99]
	global_store_dwordx4 v18, v[92:95], s[98:99]
	global_store_dwordx4 v19, v[96:99], s[98:99]
	s_waitcnt vmcnt(23)
	ds_write_b32 v14, v100 offset:0
	ds_write_b32 v14, v101 offset:4
	ds_write_b32 v14, v102 offset:8
	ds_write_b32 v14, v103 offset:12
	s_waitcnt vmcnt(22)
	ds_write_b32 v14, v104 offset:1056
	ds_write_b32 v14, v105 offset:1060
	ds_write_b32 v14, v106 offset:1064
	ds_write_b32 v14, v107 offset:1068
	s_waitcnt vmcnt(21)
	ds_write_b32 v14, v108 offset:2112
	ds_write_b32 v14, v109 offset:2116
	ds_write_b32 v14, v110 offset:2120
	ds_write_b32 v14, v111 offset:2124
	s_waitcnt vmcnt(20)
	ds_write_b32 v14, v112 offset:3168
	ds_write_b32 v14, v113 offset:3172
	ds_write_b32 v14, v114 offset:3176
	ds_write_b32 v14, v115 offset:3180
	s_waitcnt vmcnt(19)
	ds_write_b32 v14, v116 offset:4224
	ds_write_b32 v14, v117 offset:4228
	ds_write_b32 v14, v118 offset:4232
	ds_write_b32 v14, v119 offset:4236
	s_waitcnt vmcnt(18)
	ds_write_b32 v14, v120 offset:5280
	ds_write_b32 v14, v121 offset:5284
	ds_write_b32 v14, v122 offset:5288
	ds_write_b32 v14, v123 offset:5292
	s_waitcnt vmcnt(17)
	ds_write_b32 v14, v124 offset:6336
	ds_write_b32 v14, v125 offset:6340
	ds_write_b32 v14, v126 offset:6344
	ds_write_b32 v14, v127 offset:6348
	s_waitcnt vmcnt(16)
	ds_write_b32 v14, v128 offset:7392
	ds_write_b32 v14, v129 offset:7396
	ds_write_b32 v14, v130 offset:7400
	ds_write_b32 v14, v131 offset:7404
	s_add_u32 s95, s94, 0x3400
	s_lshr_b32 vcc_lo, s95, 7
	s_and_b32 vcc_hi, s95, 0x7f
	s_lshl_b32 vcc_lo, vcc_lo, 20
	s_lshl_b32 vcc_hi, vcc_hi, 7
	s_add_u32 s96, s100, vcc_lo
	s_addc_u32 s97, s101, 0
	s_add_u32 s96, s96, vcc_hi
	s_addc_u32 s97, s97, 0
	global_load_dwordx4 v[100:103], v6, s[96:97]
	global_load_dwordx4 v[104:107], v7, s[96:97]
	global_load_dwordx4 v[108:111], v8, s[96:97]
	global_load_dwordx4 v[112:115], v9, s[96:97]
	global_load_dwordx4 v[116:119], v10, s[96:97]
	global_load_dwordx4 v[120:123], v11, s[96:97]
	global_load_dwordx4 v[124:127], v12, s[96:97]
	global_load_dwordx4 v[128:131], v13, s[96:97]
	ds_read2_b32 v[52:53], v15 offset0:0 offset1:33
	ds_read2_b32 v[54:55], v15 offset0:66 offset1:99
	ds_read2_b32 v[56:57], v15 offset0:132 offset1:165
	ds_read2_b32 v[58:59], v15 offset0:198 offset1:231
	ds_read2_b32 v[60:61], v15 offset0:8 offset1:41
	ds_read2_b32 v[62:63], v15 offset0:74 offset1:107
	ds_read2_b32 v[64:65], v15 offset0:140 offset1:173
	ds_read2_b32 v[66:67], v15 offset0:206 offset1:239
	ds_read2_b32 v[68:69], v15 offset0:16 offset1:49
	ds_read2_b32 v[70:71], v15 offset0:82 offset1:115
	ds_read2_b32 v[72:73], v15 offset0:148 offset1:181
	ds_read2_b32 v[74:75], v15 offset0:214 offset1:247
	ds_read2_b32 v[76:77], v15 offset0:24 offset1:57
	ds_read2_b32 v[78:79], v15 offset0:90 offset1:123
	ds_read2_b32 v[80:81], v15 offset0:156 offset1:189
	ds_read2_b32 v[82:83], v15 offset0:222 offset1:255
	s_add_u32 s95, s94, 0x2c00
	s_lshr_b32 vcc_lo, s95, 7
	s_and_b32 vcc_hi, s95, 0x7f
	s_mul_i32 vcc_hi, vcc_hi, 0xac000
	s_lshl_b32 vcc_lo, vcc_lo, 7
	s_add_u32 s98, s66, 0x12d00000
	s_addc_u32 s99, s67, 0
	s_add_u32 s98, s98, vcc_hi
	s_addc_u32 s99, s99, 0
	s_add_u32 s98, s98, vcc_lo
	s_addc_u32 s99, s99, 0
	s_waitcnt lgkmcnt(0)
	v_cvt_pk_bf16_f32 v84, v52, v53
	v_cvt_pk_bf16_f32 v85, v54, v55
	v_cvt_pk_bf16_f32 v86, v56, v57
	v_cvt_pk_bf16_f32 v87, v58, v59
	v_cvt_pk_bf16_f32 v88, v60, v61
	v_cvt_pk_bf16_f32 v89, v62, v63
	v_cvt_pk_bf16_f32 v90, v64, v65
	v_cvt_pk_bf16_f32 v91, v66, v67
	v_cvt_pk_bf16_f32 v92, v68, v69
	v_cvt_pk_bf16_f32 v93, v70, v71
	v_cvt_pk_bf16_f32 v94, v72, v73
	v_cvt_pk_bf16_f32 v95, v74, v75
	v_cvt_pk_bf16_f32 v96, v76, v77
	v_cvt_pk_bf16_f32 v97, v78, v79
	v_cvt_pk_bf16_f32 v98, v80, v81
	v_cvt_pk_bf16_f32 v99, v82, v83
	global_store_dwordx4 v16, v[84:87], s[98:99]
	global_store_dwordx4 v17, v[88:91], s[98:99]
	global_store_dwordx4 v18, v[92:95], s[98:99]
	global_store_dwordx4 v19, v[96:99], s[98:99]
	s_waitcnt vmcnt(23)
	ds_write_b32 v14, v20 offset:0
	ds_write_b32 v14, v21 offset:4
	ds_write_b32 v14, v22 offset:8
	ds_write_b32 v14, v23 offset:12
	s_waitcnt vmcnt(22)
	ds_write_b32 v14, v24 offset:1056
	ds_write_b32 v14, v25 offset:1060
	ds_write_b32 v14, v26 offset:1064
	ds_write_b32 v14, v27 offset:1068
	s_waitcnt vmcnt(21)
	ds_write_b32 v14, v28 offset:2112
	ds_write_b32 v14, v29 offset:2116
	ds_write_b32 v14, v30 offset:2120
	ds_write_b32 v14, v31 offset:2124
	s_waitcnt vmcnt(20)
	ds_write_b32 v14, v32 offset:3168
	ds_write_b32 v14, v33 offset:3172
	ds_write_b32 v14, v34 offset:3176
	ds_write_b32 v14, v35 offset:3180
	s_waitcnt vmcnt(19)
	ds_write_b32 v14, v36 offset:4224
	ds_write_b32 v14, v37 offset:4228
	ds_write_b32 v14, v38 offset:4232
	ds_write_b32 v14, v39 offset:4236
	s_waitcnt vmcnt(18)
	ds_write_b32 v14, v40 offset:5280
	ds_write_b32 v14, v41 offset:5284
	ds_write_b32 v14, v42 offset:5288
	ds_write_b32 v14, v43 offset:5292
	s_waitcnt vmcnt(17)
	ds_write_b32 v14, v44 offset:6336
	ds_write_b32 v14, v45 offset:6340
	ds_write_b32 v14, v46 offset:6344
	ds_write_b32 v14, v47 offset:6348
	s_waitcnt vmcnt(16)
	ds_write_b32 v14, v48 offset:7392
	ds_write_b32 v14, v49 offset:7396
	ds_write_b32 v14, v50 offset:7400
	ds_write_b32 v14, v51 offset:7404
	s_add_u32 s95, s94, 0x3800
	s_lshr_b32 vcc_lo, s95, 7
	s_and_b32 vcc_hi, s95, 0x7f
	s_lshl_b32 vcc_lo, vcc_lo, 20
	s_lshl_b32 vcc_hi, vcc_hi, 7
	s_add_u32 s96, s100, vcc_lo
	s_addc_u32 s97, s101, 0
	s_add_u32 s96, s96, vcc_hi
	s_addc_u32 s97, s97, 0
	global_load_dwordx4 v[20:23], v6, s[96:97]
	global_load_dwordx4 v[24:27], v7, s[96:97]
	global_load_dwordx4 v[28:31], v8, s[96:97]
	global_load_dwordx4 v[32:35], v9, s[96:97]
	global_load_dwordx4 v[36:39], v10, s[96:97]
	global_load_dwordx4 v[40:43], v11, s[96:97]
	global_load_dwordx4 v[44:47], v12, s[96:97]
	global_load_dwordx4 v[48:51], v13, s[96:97]
	ds_read2_b32 v[52:53], v15 offset0:0 offset1:33
	ds_read2_b32 v[54:55], v15 offset0:66 offset1:99
	ds_read2_b32 v[56:57], v15 offset0:132 offset1:165
	ds_read2_b32 v[58:59], v15 offset0:198 offset1:231
	ds_read2_b32 v[60:61], v15 offset0:8 offset1:41
	ds_read2_b32 v[62:63], v15 offset0:74 offset1:107
	ds_read2_b32 v[64:65], v15 offset0:140 offset1:173
	ds_read2_b32 v[66:67], v15 offset0:206 offset1:239
	ds_read2_b32 v[68:69], v15 offset0:16 offset1:49
	ds_read2_b32 v[70:71], v15 offset0:82 offset1:115
	ds_read2_b32 v[72:73], v15 offset0:148 offset1:181
	ds_read2_b32 v[74:75], v15 offset0:214 offset1:247
	ds_read2_b32 v[76:77], v15 offset0:24 offset1:57
	ds_read2_b32 v[78:79], v15 offset0:90 offset1:123
	ds_read2_b32 v[80:81], v15 offset0:156 offset1:189
	ds_read2_b32 v[82:83], v15 offset0:222 offset1:255
	s_add_u32 s95, s94, 0x3000
	s_lshr_b32 vcc_lo, s95, 7
	s_and_b32 vcc_hi, s95, 0x7f
	s_mul_i32 vcc_hi, vcc_hi, 0xac000
	s_lshl_b32 vcc_lo, vcc_lo, 7
	s_add_u32 s98, s66, 0x12d00000
	s_addc_u32 s99, s67, 0
	s_add_u32 s98, s98, vcc_hi
	s_addc_u32 s99, s99, 0
	s_add_u32 s98, s98, vcc_lo
	s_addc_u32 s99, s99, 0
	s_waitcnt lgkmcnt(0)
	v_cvt_pk_bf16_f32 v84, v52, v53
	v_cvt_pk_bf16_f32 v85, v54, v55
	v_cvt_pk_bf16_f32 v86, v56, v57
	v_cvt_pk_bf16_f32 v87, v58, v59
	v_cvt_pk_bf16_f32 v88, v60, v61
	v_cvt_pk_bf16_f32 v89, v62, v63
	v_cvt_pk_bf16_f32 v90, v64, v65
	v_cvt_pk_bf16_f32 v91, v66, v67
	v_cvt_pk_bf16_f32 v92, v68, v69
	v_cvt_pk_bf16_f32 v93, v70, v71
	v_cvt_pk_bf16_f32 v94, v72, v73
	v_cvt_pk_bf16_f32 v95, v74, v75
	v_cvt_pk_bf16_f32 v96, v76, v77
	v_cvt_pk_bf16_f32 v97, v78, v79
	v_cvt_pk_bf16_f32 v98, v80, v81
	v_cvt_pk_bf16_f32 v99, v82, v83
	global_store_dwordx4 v16, v[84:87], s[98:99]
	global_store_dwordx4 v17, v[88:91], s[98:99]
	global_store_dwordx4 v18, v[92:95], s[98:99]
	global_store_dwordx4 v19, v[96:99], s[98:99]
	s_waitcnt vmcnt(23)
	ds_write_b32 v14, v100 offset:0
	ds_write_b32 v14, v101 offset:4
	ds_write_b32 v14, v102 offset:8
	ds_write_b32 v14, v103 offset:12
	s_waitcnt vmcnt(22)
	ds_write_b32 v14, v104 offset:1056
	ds_write_b32 v14, v105 offset:1060
	ds_write_b32 v14, v106 offset:1064
	ds_write_b32 v14, v107 offset:1068
	s_waitcnt vmcnt(21)
	ds_write_b32 v14, v108 offset:2112
	ds_write_b32 v14, v109 offset:2116
	ds_write_b32 v14, v110 offset:2120
	ds_write_b32 v14, v111 offset:2124
	s_waitcnt vmcnt(20)
	ds_write_b32 v14, v112 offset:3168
	ds_write_b32 v14, v113 offset:3172
	ds_write_b32 v14, v114 offset:3176
	ds_write_b32 v14, v115 offset:3180
	s_waitcnt vmcnt(19)
	ds_write_b32 v14, v116 offset:4224
	ds_write_b32 v14, v117 offset:4228
	ds_write_b32 v14, v118 offset:4232
	ds_write_b32 v14, v119 offset:4236
	s_waitcnt vmcnt(18)
	ds_write_b32 v14, v120 offset:5280
	ds_write_b32 v14, v121 offset:5284
	ds_write_b32 v14, v122 offset:5288
	ds_write_b32 v14, v123 offset:5292
	s_waitcnt vmcnt(17)
	ds_write_b32 v14, v124 offset:6336
	ds_write_b32 v14, v125 offset:6340
	ds_write_b32 v14, v126 offset:6344
	ds_write_b32 v14, v127 offset:6348
	s_waitcnt vmcnt(16)
	ds_write_b32 v14, v128 offset:7392
	ds_write_b32 v14, v129 offset:7396
	ds_write_b32 v14, v130 offset:7400
	ds_write_b32 v14, v131 offset:7404
	s_add_u32 s95, s94, 0x3c00
	s_lshr_b32 vcc_lo, s95, 7
	s_and_b32 vcc_hi, s95, 0x7f
	s_lshl_b32 vcc_lo, vcc_lo, 20
	s_lshl_b32 vcc_hi, vcc_hi, 7
	s_add_u32 s96, s100, vcc_lo
	s_addc_u32 s97, s101, 0
	s_add_u32 s96, s96, vcc_hi
	s_addc_u32 s97, s97, 0
	global_load_dwordx4 v[100:103], v6, s[96:97]
	global_load_dwordx4 v[104:107], v7, s[96:97]
	global_load_dwordx4 v[108:111], v8, s[96:97]
	global_load_dwordx4 v[112:115], v9, s[96:97]
	global_load_dwordx4 v[116:119], v10, s[96:97]
	global_load_dwordx4 v[120:123], v11, s[96:97]
	global_load_dwordx4 v[124:127], v12, s[96:97]
	global_load_dwordx4 v[128:131], v13, s[96:97]
	ds_read2_b32 v[52:53], v15 offset0:0 offset1:33
	ds_read2_b32 v[54:55], v15 offset0:66 offset1:99
	ds_read2_b32 v[56:57], v15 offset0:132 offset1:165
	ds_read2_b32 v[58:59], v15 offset0:198 offset1:231
	ds_read2_b32 v[60:61], v15 offset0:8 offset1:41
	ds_read2_b32 v[62:63], v15 offset0:74 offset1:107
	ds_read2_b32 v[64:65], v15 offset0:140 offset1:173
	ds_read2_b32 v[66:67], v15 offset0:206 offset1:239
	ds_read2_b32 v[68:69], v15 offset0:16 offset1:49
	ds_read2_b32 v[70:71], v15 offset0:82 offset1:115
	ds_read2_b32 v[72:73], v15 offset0:148 offset1:181
	ds_read2_b32 v[74:75], v15 offset0:214 offset1:247
	ds_read2_b32 v[76:77], v15 offset0:24 offset1:57
	ds_read2_b32 v[78:79], v15 offset0:90 offset1:123
	ds_read2_b32 v[80:81], v15 offset0:156 offset1:189
	ds_read2_b32 v[82:83], v15 offset0:222 offset1:255
	s_add_u32 s95, s94, 0x3400
	s_lshr_b32 vcc_lo, s95, 7
	s_and_b32 vcc_hi, s95, 0x7f
	s_mul_i32 vcc_hi, vcc_hi, 0xac000
	s_lshl_b32 vcc_lo, vcc_lo, 7
	s_add_u32 s98, s66, 0x12d00000
	s_addc_u32 s99, s67, 0
	s_add_u32 s98, s98, vcc_hi
	s_addc_u32 s99, s99, 0
	s_add_u32 s98, s98, vcc_lo
	s_addc_u32 s99, s99, 0
	s_waitcnt lgkmcnt(0)
	v_cvt_pk_bf16_f32 v84, v52, v53
	v_cvt_pk_bf16_f32 v85, v54, v55
	v_cvt_pk_bf16_f32 v86, v56, v57
	v_cvt_pk_bf16_f32 v87, v58, v59
	v_cvt_pk_bf16_f32 v88, v60, v61
	v_cvt_pk_bf16_f32 v89, v62, v63
	v_cvt_pk_bf16_f32 v90, v64, v65
	v_cvt_pk_bf16_f32 v91, v66, v67
	v_cvt_pk_bf16_f32 v92, v68, v69
	v_cvt_pk_bf16_f32 v93, v70, v71
	v_cvt_pk_bf16_f32 v94, v72, v73
	v_cvt_pk_bf16_f32 v95, v74, v75
	v_cvt_pk_bf16_f32 v96, v76, v77
	v_cvt_pk_bf16_f32 v97, v78, v79
	v_cvt_pk_bf16_f32 v98, v80, v81
	v_cvt_pk_bf16_f32 v99, v82, v83
	global_store_dwordx4 v16, v[84:87], s[98:99]
	global_store_dwordx4 v17, v[88:91], s[98:99]
	global_store_dwordx4 v18, v[92:95], s[98:99]
	global_store_dwordx4 v19, v[96:99], s[98:99]
	s_waitcnt vmcnt(23)
	ds_write_b32 v14, v20 offset:0
	ds_write_b32 v14, v21 offset:4
	ds_write_b32 v14, v22 offset:8
	ds_write_b32 v14, v23 offset:12
	s_waitcnt vmcnt(22)
	ds_write_b32 v14, v24 offset:1056
	ds_write_b32 v14, v25 offset:1060
	ds_write_b32 v14, v26 offset:1064
	ds_write_b32 v14, v27 offset:1068
	s_waitcnt vmcnt(21)
	ds_write_b32 v14, v28 offset:2112
	ds_write_b32 v14, v29 offset:2116
	ds_write_b32 v14, v30 offset:2120
	ds_write_b32 v14, v31 offset:2124
	s_waitcnt vmcnt(20)
	ds_write_b32 v14, v32 offset:3168
	ds_write_b32 v14, v33 offset:3172
	ds_write_b32 v14, v34 offset:3176
	ds_write_b32 v14, v35 offset:3180
	s_waitcnt vmcnt(19)
	ds_write_b32 v14, v36 offset:4224
	ds_write_b32 v14, v37 offset:4228
	ds_write_b32 v14, v38 offset:4232
	ds_write_b32 v14, v39 offset:4236
	s_waitcnt vmcnt(18)
	ds_write_b32 v14, v40 offset:5280
	ds_write_b32 v14, v41 offset:5284
	ds_write_b32 v14, v42 offset:5288
	ds_write_b32 v14, v43 offset:5292
	s_waitcnt vmcnt(17)
	ds_write_b32 v14, v44 offset:6336
	ds_write_b32 v14, v45 offset:6340
	ds_write_b32 v14, v46 offset:6344
	ds_write_b32 v14, v47 offset:6348
	s_waitcnt vmcnt(16)
	ds_write_b32 v14, v48 offset:7392
	ds_write_b32 v14, v49 offset:7396
	ds_write_b32 v14, v50 offset:7400
	ds_write_b32 v14, v51 offset:7404
	s_add_u32 s95, s94, 0x4000
	s_lshr_b32 vcc_lo, s95, 7
	s_and_b32 vcc_hi, s95, 0x7f
	s_lshl_b32 vcc_lo, vcc_lo, 20
	s_lshl_b32 vcc_hi, vcc_hi, 7
	s_add_u32 s96, s100, vcc_lo
	s_addc_u32 s97, s101, 0
	s_add_u32 s96, s96, vcc_hi
	s_addc_u32 s97, s97, 0
	global_load_dwordx4 v[20:23], v6, s[96:97]
	global_load_dwordx4 v[24:27], v7, s[96:97]
	global_load_dwordx4 v[28:31], v8, s[96:97]
	global_load_dwordx4 v[32:35], v9, s[96:97]
	global_load_dwordx4 v[36:39], v10, s[96:97]
	global_load_dwordx4 v[40:43], v11, s[96:97]
	global_load_dwordx4 v[44:47], v12, s[96:97]
	global_load_dwordx4 v[48:51], v13, s[96:97]
	ds_read2_b32 v[52:53], v15 offset0:0 offset1:33
	ds_read2_b32 v[54:55], v15 offset0:66 offset1:99
	ds_read2_b32 v[56:57], v15 offset0:132 offset1:165
	ds_read2_b32 v[58:59], v15 offset0:198 offset1:231
	ds_read2_b32 v[60:61], v15 offset0:8 offset1:41
	ds_read2_b32 v[62:63], v15 offset0:74 offset1:107
	ds_read2_b32 v[64:65], v15 offset0:140 offset1:173
	ds_read2_b32 v[66:67], v15 offset0:206 offset1:239
	ds_read2_b32 v[68:69], v15 offset0:16 offset1:49
	ds_read2_b32 v[70:71], v15 offset0:82 offset1:115
	ds_read2_b32 v[72:73], v15 offset0:148 offset1:181
	ds_read2_b32 v[74:75], v15 offset0:214 offset1:247
	ds_read2_b32 v[76:77], v15 offset0:24 offset1:57
	ds_read2_b32 v[78:79], v15 offset0:90 offset1:123
	ds_read2_b32 v[80:81], v15 offset0:156 offset1:189
	ds_read2_b32 v[82:83], v15 offset0:222 offset1:255
	s_add_u32 s95, s94, 0x3800
	s_lshr_b32 vcc_lo, s95, 7
	s_and_b32 vcc_hi, s95, 0x7f
	s_mul_i32 vcc_hi, vcc_hi, 0xac000
	s_lshl_b32 vcc_lo, vcc_lo, 7
	s_add_u32 s98, s66, 0x12d00000
	s_addc_u32 s99, s67, 0
	s_add_u32 s98, s98, vcc_hi
	s_addc_u32 s99, s99, 0
	s_add_u32 s98, s98, vcc_lo
	s_addc_u32 s99, s99, 0
	s_waitcnt lgkmcnt(0)
	v_cvt_pk_bf16_f32 v84, v52, v53
	v_cvt_pk_bf16_f32 v85, v54, v55
	v_cvt_pk_bf16_f32 v86, v56, v57
	v_cvt_pk_bf16_f32 v87, v58, v59
	v_cvt_pk_bf16_f32 v88, v60, v61
	v_cvt_pk_bf16_f32 v89, v62, v63
	v_cvt_pk_bf16_f32 v90, v64, v65
	v_cvt_pk_bf16_f32 v91, v66, v67
	v_cvt_pk_bf16_f32 v92, v68, v69
	v_cvt_pk_bf16_f32 v93, v70, v71
	v_cvt_pk_bf16_f32 v94, v72, v73
	v_cvt_pk_bf16_f32 v95, v74, v75
	v_cvt_pk_bf16_f32 v96, v76, v77
	v_cvt_pk_bf16_f32 v97, v78, v79
	v_cvt_pk_bf16_f32 v98, v80, v81
	v_cvt_pk_bf16_f32 v99, v82, v83
	global_store_dwordx4 v16, v[84:87], s[98:99]
	global_store_dwordx4 v17, v[88:91], s[98:99]
	global_store_dwordx4 v18, v[92:95], s[98:99]
	global_store_dwordx4 v19, v[96:99], s[98:99]
	s_waitcnt vmcnt(23)
	ds_write_b32 v14, v100 offset:0
	ds_write_b32 v14, v101 offset:4
	ds_write_b32 v14, v102 offset:8
	ds_write_b32 v14, v103 offset:12
	s_waitcnt vmcnt(22)
	ds_write_b32 v14, v104 offset:1056
	ds_write_b32 v14, v105 offset:1060
	ds_write_b32 v14, v106 offset:1064
	ds_write_b32 v14, v107 offset:1068
	s_waitcnt vmcnt(21)
	ds_write_b32 v14, v108 offset:2112
	ds_write_b32 v14, v109 offset:2116
	ds_write_b32 v14, v110 offset:2120
	ds_write_b32 v14, v111 offset:2124
	s_waitcnt vmcnt(20)
	ds_write_b32 v14, v112 offset:3168
	ds_write_b32 v14, v113 offset:3172
	ds_write_b32 v14, v114 offset:3176
	ds_write_b32 v14, v115 offset:3180
	s_waitcnt vmcnt(19)
	ds_write_b32 v14, v116 offset:4224
	ds_write_b32 v14, v117 offset:4228
	ds_write_b32 v14, v118 offset:4232
	ds_write_b32 v14, v119 offset:4236
	s_waitcnt vmcnt(18)
	ds_write_b32 v14, v120 offset:5280
	ds_write_b32 v14, v121 offset:5284
	ds_write_b32 v14, v122 offset:5288
	ds_write_b32 v14, v123 offset:5292
	s_waitcnt vmcnt(17)
	ds_write_b32 v14, v124 offset:6336
	ds_write_b32 v14, v125 offset:6340
	ds_write_b32 v14, v126 offset:6344
	ds_write_b32 v14, v127 offset:6348
	s_waitcnt vmcnt(16)
	ds_write_b32 v14, v128 offset:7392
	ds_write_b32 v14, v129 offset:7396
	ds_write_b32 v14, v130 offset:7400
	ds_write_b32 v14, v131 offset:7404
	s_add_u32 s95, s94, 0x4400
	s_lshr_b32 vcc_lo, s95, 7
	s_and_b32 vcc_hi, s95, 0x7f
	s_lshl_b32 vcc_lo, vcc_lo, 20
	s_lshl_b32 vcc_hi, vcc_hi, 7
	s_add_u32 s96, s100, vcc_lo
	s_addc_u32 s97, s101, 0
	s_add_u32 s96, s96, vcc_hi
	s_addc_u32 s97, s97, 0
	global_load_dwordx4 v[100:103], v6, s[96:97]
	global_load_dwordx4 v[104:107], v7, s[96:97]
	global_load_dwordx4 v[108:111], v8, s[96:97]
	global_load_dwordx4 v[112:115], v9, s[96:97]
	global_load_dwordx4 v[116:119], v10, s[96:97]
	global_load_dwordx4 v[120:123], v11, s[96:97]
	global_load_dwordx4 v[124:127], v12, s[96:97]
	global_load_dwordx4 v[128:131], v13, s[96:97]
	ds_read2_b32 v[52:53], v15 offset0:0 offset1:33
	ds_read2_b32 v[54:55], v15 offset0:66 offset1:99
	ds_read2_b32 v[56:57], v15 offset0:132 offset1:165
	ds_read2_b32 v[58:59], v15 offset0:198 offset1:231
	ds_read2_b32 v[60:61], v15 offset0:8 offset1:41
	ds_read2_b32 v[62:63], v15 offset0:74 offset1:107
	ds_read2_b32 v[64:65], v15 offset0:140 offset1:173
	ds_read2_b32 v[66:67], v15 offset0:206 offset1:239
	ds_read2_b32 v[68:69], v15 offset0:16 offset1:49
	ds_read2_b32 v[70:71], v15 offset0:82 offset1:115
	ds_read2_b32 v[72:73], v15 offset0:148 offset1:181
	ds_read2_b32 v[74:75], v15 offset0:214 offset1:247
	ds_read2_b32 v[76:77], v15 offset0:24 offset1:57
	ds_read2_b32 v[78:79], v15 offset0:90 offset1:123
	ds_read2_b32 v[80:81], v15 offset0:156 offset1:189
	ds_read2_b32 v[82:83], v15 offset0:222 offset1:255
	s_add_u32 s95, s94, 0x3c00
	s_lshr_b32 vcc_lo, s95, 7
	s_and_b32 vcc_hi, s95, 0x7f
	s_mul_i32 vcc_hi, vcc_hi, 0xac000
	s_lshl_b32 vcc_lo, vcc_lo, 7
	s_add_u32 s98, s66, 0x12d00000
	s_addc_u32 s99, s67, 0
	s_add_u32 s98, s98, vcc_hi
	s_addc_u32 s99, s99, 0
	s_add_u32 s98, s98, vcc_lo
	s_addc_u32 s99, s99, 0
	s_waitcnt lgkmcnt(0)
	v_cvt_pk_bf16_f32 v84, v52, v53
	v_cvt_pk_bf16_f32 v85, v54, v55
	v_cvt_pk_bf16_f32 v86, v56, v57
	v_cvt_pk_bf16_f32 v87, v58, v59
	v_cvt_pk_bf16_f32 v88, v60, v61
	v_cvt_pk_bf16_f32 v89, v62, v63
	v_cvt_pk_bf16_f32 v90, v64, v65
	v_cvt_pk_bf16_f32 v91, v66, v67
	v_cvt_pk_bf16_f32 v92, v68, v69
	v_cvt_pk_bf16_f32 v93, v70, v71
	v_cvt_pk_bf16_f32 v94, v72, v73
	v_cvt_pk_bf16_f32 v95, v74, v75
	v_cvt_pk_bf16_f32 v96, v76, v77
	v_cvt_pk_bf16_f32 v97, v78, v79
	v_cvt_pk_bf16_f32 v98, v80, v81
	v_cvt_pk_bf16_f32 v99, v82, v83
	global_store_dwordx4 v16, v[84:87], s[98:99]
	global_store_dwordx4 v17, v[88:91], s[98:99]
	global_store_dwordx4 v18, v[92:95], s[98:99]
	global_store_dwordx4 v19, v[96:99], s[98:99]
	s_waitcnt vmcnt(23)
	ds_write_b32 v14, v20 offset:0
	ds_write_b32 v14, v21 offset:4
	ds_write_b32 v14, v22 offset:8
	ds_write_b32 v14, v23 offset:12
	s_waitcnt vmcnt(22)
	ds_write_b32 v14, v24 offset:1056
	ds_write_b32 v14, v25 offset:1060
	ds_write_b32 v14, v26 offset:1064
	ds_write_b32 v14, v27 offset:1068
	s_waitcnt vmcnt(21)
	ds_write_b32 v14, v28 offset:2112
	ds_write_b32 v14, v29 offset:2116
	ds_write_b32 v14, v30 offset:2120
	ds_write_b32 v14, v31 offset:2124
	s_waitcnt vmcnt(20)
	ds_write_b32 v14, v32 offset:3168
	ds_write_b32 v14, v33 offset:3172
	ds_write_b32 v14, v34 offset:3176
	ds_write_b32 v14, v35 offset:3180
	s_waitcnt vmcnt(19)
	ds_write_b32 v14, v36 offset:4224
	ds_write_b32 v14, v37 offset:4228
	ds_write_b32 v14, v38 offset:4232
	ds_write_b32 v14, v39 offset:4236
	s_waitcnt vmcnt(18)
	ds_write_b32 v14, v40 offset:5280
	ds_write_b32 v14, v41 offset:5284
	ds_write_b32 v14, v42 offset:5288
	ds_write_b32 v14, v43 offset:5292
	s_waitcnt vmcnt(17)
	ds_write_b32 v14, v44 offset:6336
	ds_write_b32 v14, v45 offset:6340
	ds_write_b32 v14, v46 offset:6344
	ds_write_b32 v14, v47 offset:6348
	s_waitcnt vmcnt(16)
	ds_write_b32 v14, v48 offset:7392
	ds_write_b32 v14, v49 offset:7396
	ds_write_b32 v14, v50 offset:7400
	ds_write_b32 v14, v51 offset:7404
	s_add_u32 s95, s94, 0x4800
	s_lshr_b32 vcc_lo, s95, 7
	s_and_b32 vcc_hi, s95, 0x7f
	s_lshl_b32 vcc_lo, vcc_lo, 20
	s_lshl_b32 vcc_hi, vcc_hi, 7
	s_add_u32 s96, s100, vcc_lo
	s_addc_u32 s97, s101, 0
	s_add_u32 s96, s96, vcc_hi
	s_addc_u32 s97, s97, 0
	global_load_dwordx4 v[20:23], v6, s[96:97]
	global_load_dwordx4 v[24:27], v7, s[96:97]
	global_load_dwordx4 v[28:31], v8, s[96:97]
	global_load_dwordx4 v[32:35], v9, s[96:97]
	global_load_dwordx4 v[36:39], v10, s[96:97]
	global_load_dwordx4 v[40:43], v11, s[96:97]
	global_load_dwordx4 v[44:47], v12, s[96:97]
	global_load_dwordx4 v[48:51], v13, s[96:97]
	ds_read2_b32 v[52:53], v15 offset0:0 offset1:33
	ds_read2_b32 v[54:55], v15 offset0:66 offset1:99
	ds_read2_b32 v[56:57], v15 offset0:132 offset1:165
	ds_read2_b32 v[58:59], v15 offset0:198 offset1:231
	ds_read2_b32 v[60:61], v15 offset0:8 offset1:41
	ds_read2_b32 v[62:63], v15 offset0:74 offset1:107
	ds_read2_b32 v[64:65], v15 offset0:140 offset1:173
	ds_read2_b32 v[66:67], v15 offset0:206 offset1:239
	ds_read2_b32 v[68:69], v15 offset0:16 offset1:49
	ds_read2_b32 v[70:71], v15 offset0:82 offset1:115
	ds_read2_b32 v[72:73], v15 offset0:148 offset1:181
	ds_read2_b32 v[74:75], v15 offset0:214 offset1:247
	ds_read2_b32 v[76:77], v15 offset0:24 offset1:57
	ds_read2_b32 v[78:79], v15 offset0:90 offset1:123
	ds_read2_b32 v[80:81], v15 offset0:156 offset1:189
	ds_read2_b32 v[82:83], v15 offset0:222 offset1:255
	s_add_u32 s95, s94, 0x4000
	s_lshr_b32 vcc_lo, s95, 7
	s_and_b32 vcc_hi, s95, 0x7f
	s_mul_i32 vcc_hi, vcc_hi, 0xac000
	s_lshl_b32 vcc_lo, vcc_lo, 7
	s_add_u32 s98, s66, 0x12d00000
	s_addc_u32 s99, s67, 0
	s_add_u32 s98, s98, vcc_hi
	s_addc_u32 s99, s99, 0
	s_add_u32 s98, s98, vcc_lo
	s_addc_u32 s99, s99, 0
	s_waitcnt lgkmcnt(0)
	v_cvt_pk_bf16_f32 v84, v52, v53
	v_cvt_pk_bf16_f32 v85, v54, v55
	v_cvt_pk_bf16_f32 v86, v56, v57
	v_cvt_pk_bf16_f32 v87, v58, v59
	v_cvt_pk_bf16_f32 v88, v60, v61
	v_cvt_pk_bf16_f32 v89, v62, v63
	v_cvt_pk_bf16_f32 v90, v64, v65
	v_cvt_pk_bf16_f32 v91, v66, v67
	v_cvt_pk_bf16_f32 v92, v68, v69
	v_cvt_pk_bf16_f32 v93, v70, v71
	v_cvt_pk_bf16_f32 v94, v72, v73
	v_cvt_pk_bf16_f32 v95, v74, v75
	v_cvt_pk_bf16_f32 v96, v76, v77
	v_cvt_pk_bf16_f32 v97, v78, v79
	v_cvt_pk_bf16_f32 v98, v80, v81
	v_cvt_pk_bf16_f32 v99, v82, v83
	global_store_dwordx4 v16, v[84:87], s[98:99]
	global_store_dwordx4 v17, v[88:91], s[98:99]
	global_store_dwordx4 v18, v[92:95], s[98:99]
	global_store_dwordx4 v19, v[96:99], s[98:99]
	s_waitcnt vmcnt(23)
	ds_write_b32 v14, v100 offset:0
	ds_write_b32 v14, v101 offset:4
	ds_write_b32 v14, v102 offset:8
	ds_write_b32 v14, v103 offset:12
	s_waitcnt vmcnt(22)
	ds_write_b32 v14, v104 offset:1056
	ds_write_b32 v14, v105 offset:1060
	ds_write_b32 v14, v106 offset:1064
	ds_write_b32 v14, v107 offset:1068
	s_waitcnt vmcnt(21)
	ds_write_b32 v14, v108 offset:2112
	ds_write_b32 v14, v109 offset:2116
	ds_write_b32 v14, v110 offset:2120
	ds_write_b32 v14, v111 offset:2124
	s_waitcnt vmcnt(20)
	ds_write_b32 v14, v112 offset:3168
	ds_write_b32 v14, v113 offset:3172
	ds_write_b32 v14, v114 offset:3176
	ds_write_b32 v14, v115 offset:3180
	s_waitcnt vmcnt(19)
	ds_write_b32 v14, v116 offset:4224
	ds_write_b32 v14, v117 offset:4228
	ds_write_b32 v14, v118 offset:4232
	ds_write_b32 v14, v119 offset:4236
	s_waitcnt vmcnt(18)
	ds_write_b32 v14, v120 offset:5280
	ds_write_b32 v14, v121 offset:5284
	ds_write_b32 v14, v122 offset:5288
	ds_write_b32 v14, v123 offset:5292
	s_waitcnt vmcnt(17)
	ds_write_b32 v14, v124 offset:6336
	ds_write_b32 v14, v125 offset:6340
	ds_write_b32 v14, v126 offset:6344
	ds_write_b32 v14, v127 offset:6348
	s_waitcnt vmcnt(16)
	ds_write_b32 v14, v128 offset:7392
	ds_write_b32 v14, v129 offset:7396
	ds_write_b32 v14, v130 offset:7400
	ds_write_b32 v14, v131 offset:7404
	s_add_u32 s95, s94, 0x4c00
	s_lshr_b32 vcc_lo, s95, 7
	s_and_b32 vcc_hi, s95, 0x7f
	s_lshl_b32 vcc_lo, vcc_lo, 20
	s_lshl_b32 vcc_hi, vcc_hi, 7
	s_add_u32 s96, s100, vcc_lo
	s_addc_u32 s97, s101, 0
	s_add_u32 s96, s96, vcc_hi
	s_addc_u32 s97, s97, 0
	global_load_dwordx4 v[100:103], v6, s[96:97]
	global_load_dwordx4 v[104:107], v7, s[96:97]
	global_load_dwordx4 v[108:111], v8, s[96:97]
	global_load_dwordx4 v[112:115], v9, s[96:97]
	global_load_dwordx4 v[116:119], v10, s[96:97]
	global_load_dwordx4 v[120:123], v11, s[96:97]
	global_load_dwordx4 v[124:127], v12, s[96:97]
	global_load_dwordx4 v[128:131], v13, s[96:97]
	ds_read2_b32 v[52:53], v15 offset0:0 offset1:33
	ds_read2_b32 v[54:55], v15 offset0:66 offset1:99
	ds_read2_b32 v[56:57], v15 offset0:132 offset1:165
	ds_read2_b32 v[58:59], v15 offset0:198 offset1:231
	ds_read2_b32 v[60:61], v15 offset0:8 offset1:41
	ds_read2_b32 v[62:63], v15 offset0:74 offset1:107
	ds_read2_b32 v[64:65], v15 offset0:140 offset1:173
	ds_read2_b32 v[66:67], v15 offset0:206 offset1:239
	ds_read2_b32 v[68:69], v15 offset0:16 offset1:49
	ds_read2_b32 v[70:71], v15 offset0:82 offset1:115
	ds_read2_b32 v[72:73], v15 offset0:148 offset1:181
	ds_read2_b32 v[74:75], v15 offset0:214 offset1:247
	ds_read2_b32 v[76:77], v15 offset0:24 offset1:57
	ds_read2_b32 v[78:79], v15 offset0:90 offset1:123
	ds_read2_b32 v[80:81], v15 offset0:156 offset1:189
	ds_read2_b32 v[82:83], v15 offset0:222 offset1:255
	s_add_u32 s95, s94, 0x4400
	s_lshr_b32 vcc_lo, s95, 7
	s_and_b32 vcc_hi, s95, 0x7f
	s_mul_i32 vcc_hi, vcc_hi, 0xac000
	s_lshl_b32 vcc_lo, vcc_lo, 7
	s_add_u32 s98, s66, 0x12d00000
	s_addc_u32 s99, s67, 0
	s_add_u32 s98, s98, vcc_hi
	s_addc_u32 s99, s99, 0
	s_add_u32 s98, s98, vcc_lo
	s_addc_u32 s99, s99, 0
	s_waitcnt lgkmcnt(0)
	v_cvt_pk_bf16_f32 v84, v52, v53
	v_cvt_pk_bf16_f32 v85, v54, v55
	v_cvt_pk_bf16_f32 v86, v56, v57
	v_cvt_pk_bf16_f32 v87, v58, v59
	v_cvt_pk_bf16_f32 v88, v60, v61
	v_cvt_pk_bf16_f32 v89, v62, v63
	v_cvt_pk_bf16_f32 v90, v64, v65
	v_cvt_pk_bf16_f32 v91, v66, v67
	v_cvt_pk_bf16_f32 v92, v68, v69
	v_cvt_pk_bf16_f32 v93, v70, v71
	v_cvt_pk_bf16_f32 v94, v72, v73
	v_cvt_pk_bf16_f32 v95, v74, v75
	v_cvt_pk_bf16_f32 v96, v76, v77
	v_cvt_pk_bf16_f32 v97, v78, v79
	v_cvt_pk_bf16_f32 v98, v80, v81
	v_cvt_pk_bf16_f32 v99, v82, v83
	global_store_dwordx4 v16, v[84:87], s[98:99]
	global_store_dwordx4 v17, v[88:91], s[98:99]
	global_store_dwordx4 v18, v[92:95], s[98:99]
	global_store_dwordx4 v19, v[96:99], s[98:99]
	s_waitcnt vmcnt(23)
	ds_write_b32 v14, v20 offset:0
	ds_write_b32 v14, v21 offset:4
	ds_write_b32 v14, v22 offset:8
	ds_write_b32 v14, v23 offset:12
	s_waitcnt vmcnt(22)
	ds_write_b32 v14, v24 offset:1056
	ds_write_b32 v14, v25 offset:1060
	ds_write_b32 v14, v26 offset:1064
	ds_write_b32 v14, v27 offset:1068
	s_waitcnt vmcnt(21)
	ds_write_b32 v14, v28 offset:2112
	ds_write_b32 v14, v29 offset:2116
	ds_write_b32 v14, v30 offset:2120
	ds_write_b32 v14, v31 offset:2124
	s_waitcnt vmcnt(20)
	ds_write_b32 v14, v32 offset:3168
	ds_write_b32 v14, v33 offset:3172
	ds_write_b32 v14, v34 offset:3176
	ds_write_b32 v14, v35 offset:3180
	s_waitcnt vmcnt(19)
	ds_write_b32 v14, v36 offset:4224
	ds_write_b32 v14, v37 offset:4228
	ds_write_b32 v14, v38 offset:4232
	ds_write_b32 v14, v39 offset:4236
	s_waitcnt vmcnt(18)
	ds_write_b32 v14, v40 offset:5280
	ds_write_b32 v14, v41 offset:5284
	ds_write_b32 v14, v42 offset:5288
	ds_write_b32 v14, v43 offset:5292
	s_waitcnt vmcnt(17)
	ds_write_b32 v14, v44 offset:6336
	ds_write_b32 v14, v45 offset:6340
	ds_write_b32 v14, v46 offset:6344
	ds_write_b32 v14, v47 offset:6348
	s_waitcnt vmcnt(16)
	ds_write_b32 v14, v48 offset:7392
	ds_write_b32 v14, v49 offset:7396
	ds_write_b32 v14, v50 offset:7400
	ds_write_b32 v14, v51 offset:7404
	ds_read2_b32 v[52:53], v15 offset0:0 offset1:33
	ds_read2_b32 v[54:55], v15 offset0:66 offset1:99
	ds_read2_b32 v[56:57], v15 offset0:132 offset1:165
	ds_read2_b32 v[58:59], v15 offset0:198 offset1:231
	ds_read2_b32 v[60:61], v15 offset0:8 offset1:41
	ds_read2_b32 v[62:63], v15 offset0:74 offset1:107
	ds_read2_b32 v[64:65], v15 offset0:140 offset1:173
	ds_read2_b32 v[66:67], v15 offset0:206 offset1:239
	ds_read2_b32 v[68:69], v15 offset0:16 offset1:49
	ds_read2_b32 v[70:71], v15 offset0:82 offset1:115
	ds_read2_b32 v[72:73], v15 offset0:148 offset1:181
	ds_read2_b32 v[74:75], v15 offset0:214 offset1:247
	ds_read2_b32 v[76:77], v15 offset0:24 offset1:57
	ds_read2_b32 v[78:79], v15 offset0:90 offset1:123
	ds_read2_b32 v[80:81], v15 offset0:156 offset1:189
	ds_read2_b32 v[82:83], v15 offset0:222 offset1:255
	s_add_u32 s95, s94, 0x4800
	s_lshr_b32 vcc_lo, s95, 7
	s_and_b32 vcc_hi, s95, 0x7f
	s_mul_i32 vcc_hi, vcc_hi, 0xac000
	s_lshl_b32 vcc_lo, vcc_lo, 7
	s_add_u32 s98, s66, 0x12d00000
	s_addc_u32 s99, s67, 0
	s_add_u32 s98, s98, vcc_hi
	s_addc_u32 s99, s99, 0
	s_add_u32 s98, s98, vcc_lo
	s_addc_u32 s99, s99, 0
	s_waitcnt lgkmcnt(0)
	v_cvt_pk_bf16_f32 v84, v52, v53
	v_cvt_pk_bf16_f32 v85, v54, v55
	v_cvt_pk_bf16_f32 v86, v56, v57
	v_cvt_pk_bf16_f32 v87, v58, v59
	v_cvt_pk_bf16_f32 v88, v60, v61
	v_cvt_pk_bf16_f32 v89, v62, v63
	v_cvt_pk_bf16_f32 v90, v64, v65
	v_cvt_pk_bf16_f32 v91, v66, v67
	v_cvt_pk_bf16_f32 v92, v68, v69
	v_cvt_pk_bf16_f32 v93, v70, v71
	v_cvt_pk_bf16_f32 v94, v72, v73
	v_cvt_pk_bf16_f32 v95, v74, v75
	v_cvt_pk_bf16_f32 v96, v76, v77
	v_cvt_pk_bf16_f32 v97, v78, v79
	v_cvt_pk_bf16_f32 v98, v80, v81
	v_cvt_pk_bf16_f32 v99, v82, v83
	global_store_dwordx4 v16, v[84:87], s[98:99]
	global_store_dwordx4 v17, v[88:91], s[98:99]
	global_store_dwordx4 v18, v[92:95], s[98:99]
	global_store_dwordx4 v19, v[96:99], s[98:99]
	s_waitcnt vmcnt(15)
	ds_write_b32 v14, v100 offset:0
	ds_write_b32 v14, v101 offset:4
	ds_write_b32 v14, v102 offset:8
	ds_write_b32 v14, v103 offset:12
	s_waitcnt vmcnt(14)
	ds_write_b32 v14, v104 offset:1056
	ds_write_b32 v14, v105 offset:1060
	ds_write_b32 v14, v106 offset:1064
	ds_write_b32 v14, v107 offset:1068
	s_waitcnt vmcnt(13)
	ds_write_b32 v14, v108 offset:2112
	ds_write_b32 v14, v109 offset:2116
	ds_write_b32 v14, v110 offset:2120
	ds_write_b32 v14, v111 offset:2124
	s_waitcnt vmcnt(12)
	ds_write_b32 v14, v112 offset:3168
	ds_write_b32 v14, v113 offset:3172
	ds_write_b32 v14, v114 offset:3176
	ds_write_b32 v14, v115 offset:3180
	s_waitcnt vmcnt(11)
	ds_write_b32 v14, v116 offset:4224
	ds_write_b32 v14, v117 offset:4228
	ds_write_b32 v14, v118 offset:4232
	ds_write_b32 v14, v119 offset:4236
	s_waitcnt vmcnt(10)
	ds_write_b32 v14, v120 offset:5280
	ds_write_b32 v14, v121 offset:5284
	ds_write_b32 v14, v122 offset:5288
	ds_write_b32 v14, v123 offset:5292
	s_waitcnt vmcnt(9)
	ds_write_b32 v14, v124 offset:6336
	ds_write_b32 v14, v125 offset:6340
	ds_write_b32 v14, v126 offset:6344
	ds_write_b32 v14, v127 offset:6348
	s_waitcnt vmcnt(8)
	ds_write_b32 v14, v128 offset:7392
	ds_write_b32 v14, v129 offset:7396
	ds_write_b32 v14, v130 offset:7400
	ds_write_b32 v14, v131 offset:7404
	ds_read2_b32 v[52:53], v15 offset0:0 offset1:33
	ds_read2_b32 v[54:55], v15 offset0:66 offset1:99
	ds_read2_b32 v[56:57], v15 offset0:132 offset1:165
	ds_read2_b32 v[58:59], v15 offset0:198 offset1:231
	ds_read2_b32 v[60:61], v15 offset0:8 offset1:41
	ds_read2_b32 v[62:63], v15 offset0:74 offset1:107
	ds_read2_b32 v[64:65], v15 offset0:140 offset1:173
	ds_read2_b32 v[66:67], v15 offset0:206 offset1:239
	ds_read2_b32 v[68:69], v15 offset0:16 offset1:49
	ds_read2_b32 v[70:71], v15 offset0:82 offset1:115
	ds_read2_b32 v[72:73], v15 offset0:148 offset1:181
	ds_read2_b32 v[74:75], v15 offset0:214 offset1:247
	ds_read2_b32 v[76:77], v15 offset0:24 offset1:57
	ds_read2_b32 v[78:79], v15 offset0:90 offset1:123
	ds_read2_b32 v[80:81], v15 offset0:156 offset1:189
	ds_read2_b32 v[82:83], v15 offset0:222 offset1:255
	s_add_u32 s95, s94, 0x4c00
	s_lshr_b32 vcc_lo, s95, 7
	s_and_b32 vcc_hi, s95, 0x7f
	s_mul_i32 vcc_hi, vcc_hi, 0xac000
	s_lshl_b32 vcc_lo, vcc_lo, 7
	s_add_u32 s98, s66, 0x12d00000
	s_addc_u32 s99, s67, 0
	s_add_u32 s98, s98, vcc_hi
	s_addc_u32 s99, s99, 0
	s_add_u32 s98, s98, vcc_lo
	s_addc_u32 s99, s99, 0
	s_waitcnt lgkmcnt(0)
	v_cvt_pk_bf16_f32 v84, v52, v53
	v_cvt_pk_bf16_f32 v85, v54, v55
	v_cvt_pk_bf16_f32 v86, v56, v57
	v_cvt_pk_bf16_f32 v87, v58, v59
	v_cvt_pk_bf16_f32 v88, v60, v61
	v_cvt_pk_bf16_f32 v89, v62, v63
	v_cvt_pk_bf16_f32 v90, v64, v65
	v_cvt_pk_bf16_f32 v91, v66, v67
	v_cvt_pk_bf16_f32 v92, v68, v69
	v_cvt_pk_bf16_f32 v93, v70, v71
	v_cvt_pk_bf16_f32 v94, v72, v73
	v_cvt_pk_bf16_f32 v95, v74, v75
	v_cvt_pk_bf16_f32 v96, v76, v77
	v_cvt_pk_bf16_f32 v97, v78, v79
	v_cvt_pk_bf16_f32 v98, v80, v81
	v_cvt_pk_bf16_f32 v99, v82, v83
	global_store_dwordx4 v16, v[84:87], s[98:99]
	global_store_dwordx4 v17, v[88:91], s[98:99]
	global_store_dwordx4 v18, v[92:95], s[98:99]
	global_store_dwordx4 v19, v[96:99], s[98:99]
